# fused norm: row partials stored [row][16 slots] so the 16 lanes of a row read one 64-byte record (was 16 scattered lines per row)
# speedup vs baseline: 1.0145x; 1.0025x over previous
.LBB0_57:
	s_cmp_gt_i32 s68, 0
	s_waitcnt vmcnt(6)
	s_cselect_b32 s69, -1, 2
	s_mul_i32 s70, s68, 0x6000
	s_waitcnt lgkmcnt(0)
	s_add_i32 s69, s69, s68
	v_add_u32_e32 v135, s70, v149
	v_add_u32_e32 v0, s70, v148
	s_mulk_i32 s69, 0x6000
	v_add_u32_e32 v164, v135, v152
	s_barrier
	v_lshl_add_u64 v[180:181], v[138:139], 0, s[0:1]
	v_add_u32_e32 v159, s69, v146
	v_lshl_add_u64 v[184:185], v[136:137], 0, s[0:1]
	v_add_u32_e32 v192, s69, v147
	v_add_u32_e32 v176, v0, v152
	ds_read_b128 v[140:143], v176
	ds_read_b128 v[160:163], v164
	ds_read_b128 v[164:167], v164 offset:2048
	v_lshl_add_u64 v[182:183], v[180:181], 0, s[88:89]
	v_lshl_add_u64 v[186:187], v[184:185], 0, s[88:89]
	v_add_u32_e32 v193, 0x4000, v192
	v_lshl_add_u64 v[188:189], v[180:181], 0, s[90:91]
	v_add_u32_e32 v194, 0x400, v159
	v_lshl_add_u64 v[190:191], v[180:181], 0, s[78:79]
	v_add_u32_e32 v195, 0x800, v159
	ds_read_b128 v[168:171], v176 offset:2048
	ds_read_b128 v[172:175], v176 offset:4096
	ds_read_b128 v[176:179], v176 offset:6144
	s_waitcnt lgkmcnt(3)
	s_setprio 1
	v_mfma_f32_32x32x16_bf16 v[114:129], v[140:143], v[160:163], v[114:129]
	v_mfma_f32_32x32x16_bf16 v[98:113], v[140:143], v[164:167], v[98:113]
	v_readfirstlane_b32 s69, v159
	s_mov_b32 m0, s69
	s_nop 0
	global_load_lds_dwordx4 v[182:183], off
	s_waitcnt lgkmcnt(2)
	v_mfma_f32_32x32x16_bf16 v[82:97], v[168:171], v[160:163], v[82:97]
	v_mfma_f32_32x32x16_bf16 v[66:81], v[168:171], v[164:167], v[66:81]
	v_readfirstlane_b32 s69, v194
	s_mov_b32 m0, s69
	s_nop 0
	global_load_lds_dwordx4 v[188:189], off
	s_waitcnt lgkmcnt(1)
	v_mfma_f32_32x32x16_bf16 v[50:65], v[172:175], v[160:163], v[50:65]
	v_mfma_f32_32x32x16_bf16 v[34:49], v[172:175], v[164:167], v[34:49]
	v_readfirstlane_b32 s69, v195
	s_mov_b32 m0, s69
	s_nop 0
	global_load_lds_dwordx4 v[190:191], off
	s_waitcnt lgkmcnt(0)
	v_mfma_f32_32x32x16_bf16 v[18:33], v[176:179], v[160:163], v[18:33]
	v_mfma_f32_32x32x16_bf16 v[2:17], v[176:179], v[164:167], v[2:17]
	s_setprio 0
	v_add_u32_e32 v0, v0, v153
	v_add_u32_e32 v135, v135, v153
	ds_read_b128 v[140:143], v0
	ds_read_b128 v[160:163], v135
	ds_read_b128 v[164:167], v135 offset:2048
	ds_read_b128 v[168:171], v0 offset:2048
	ds_read_b128 v[172:175], v0 offset:4096
	ds_read_b128 v[176:179], v0 offset:6144
	s_waitcnt lgkmcnt(3)
	s_setprio 1
	v_mfma_f32_32x32x16_bf16 v[114:129], v[140:143], v[160:163], v[114:129]
	v_mfma_f32_32x32x16_bf16 v[98:113], v[140:143], v[164:167], v[98:113]
	v_add_u32_e32 v0, 0xc00, v159
	v_lshl_add_u64 v[140:141], v[180:181], 0, s[76:77]
	v_readfirstlane_b32 s69, v0
	s_mov_b32 m0, s69
	s_nop 0
	global_load_lds_dwordx4 v[140:141], off
	s_waitcnt lgkmcnt(2)
	v_mfma_f32_32x32x16_bf16 v[82:97], v[168:171], v[160:163], v[82:97]
	v_mfma_f32_32x32x16_bf16 v[66:81], v[168:171], v[164:167], v[66:81]
	v_readfirstlane_b32 s69, v193
	s_mov_b32 m0, s69
	s_nop 0
	global_load_lds_dwordx4 v[186:187], off
	s_waitcnt lgkmcnt(1)
	v_mfma_f32_32x32x16_bf16 v[50:65], v[172:175], v[160:163], v[50:65]
	v_mfma_f32_32x32x16_bf16 v[34:49], v[172:175], v[164:167], v[34:49]
	v_add_u32_e32 v0, 0x4400, v192
	v_lshl_add_u64 v[140:141], v[184:185], 0, s[90:91]
	v_readfirstlane_b32 s69, v0
	s_mov_b32 m0, s69
	s_nop 0
	global_load_lds_dwordx4 v[140:141], off
	s_waitcnt lgkmcnt(0)
	v_mfma_f32_32x32x16_bf16 v[18:33], v[176:179], v[160:163], v[18:33]
	v_mfma_f32_32x32x16_bf16 v[2:17], v[176:179], v[164:167], v[2:17]
	s_setprio 0
	s_add_i32 s69, s68, 1
	s_cmp_lt_i32 s68, 2
	s_cselect_b32 s68, s69, 0
	s_add_u32 s0, s0, 0x80
	s_addc_u32 s1, s1, 0
	s_cmpk_eq_i32 s0, 0xf00
	s_cbranch_scc0 .LBB0_57
	s_waitcnt vmcnt(6)
	s_mul_i32 s0, s68, 0x6000
	s_waitcnt lgkmcnt(0)
	v_add_u32_e32 v135, s0, v149
	v_add_u32_e32 v0, s0, v148
	v_add_u32_e32 v160, v135, v152
	s_barrier
	v_add_u32_e32 v159, v0, v152
	ds_read_b128 v[136:139], v159
	ds_read_b128 v[140:143], v160
	ds_read_b128 v[160:163], v160 offset:2048
	ds_read_b128 v[164:167], v159 offset:2048
	ds_read_b128 v[168:171], v159 offset:4096
	ds_read_b128 v[172:175], v159 offset:6144
	s_waitcnt lgkmcnt(3)
	s_setprio 1
	v_mfma_f32_32x32x16_bf16 v[114:129], v[136:139], v[140:143], v[114:129]
	v_mfma_f32_32x32x16_bf16 v[98:113], v[136:139], v[160:163], v[98:113]
	s_waitcnt lgkmcnt(2)
	v_mfma_f32_32x32x16_bf16 v[82:97], v[164:167], v[140:143], v[82:97]
	v_mfma_f32_32x32x16_bf16 v[66:81], v[164:167], v[160:163], v[66:81]
	s_waitcnt lgkmcnt(1)
	v_mfma_f32_32x32x16_bf16 v[50:65], v[168:171], v[140:143], v[50:65]
	v_mfma_f32_32x32x16_bf16 v[34:49], v[168:171], v[160:163], v[34:49]
	s_waitcnt lgkmcnt(0)
	v_mfma_f32_32x32x16_bf16 v[18:33], v[172:175], v[140:143], v[18:33]
	v_mfma_f32_32x32x16_bf16 v[2:17], v[172:175], v[160:163], v[2:17]
	s_setprio 0
	v_add_u32_e32 v0, v0, v153
	v_add_u32_e32 v135, v135, v153
	ds_read_b128 v[136:139], v0
	ds_read_b128 v[140:143], v135
	ds_read_b128 v[160:163], v135 offset:2048
	ds_read_b128 v[164:167], v0 offset:2048
	ds_read_b128 v[168:171], v0 offset:4096
	ds_read_b128 v[172:175], v0 offset:6144
	s_waitcnt lgkmcnt(3)
	s_setprio 1
	v_mfma_f32_32x32x16_bf16 v[114:129], v[136:139], v[140:143], v[114:129]
	v_mfma_f32_32x32x16_bf16 v[98:113], v[136:139], v[160:163], v[98:113]
	s_waitcnt lgkmcnt(2)
	v_mfma_f32_32x32x16_bf16 v[82:97], v[164:167], v[140:143], v[82:97]
	v_mfma_f32_32x32x16_bf16 v[66:81], v[164:167], v[160:163], v[66:81]
	s_waitcnt lgkmcnt(1)
	v_mfma_f32_32x32x16_bf16 v[50:65], v[168:171], v[140:143], v[50:65]
	v_mfma_f32_32x32x16_bf16 v[34:49], v[168:171], v[160:163], v[34:49]
	s_waitcnt lgkmcnt(0)
	v_mfma_f32_32x32x16_bf16 v[18:33], v[172:175], v[140:143], v[18:33]
	v_mfma_f32_32x32x16_bf16 v[2:17], v[172:175], v[160:163], v[2:17]
	s_setprio 0
	s_waitcnt vmcnt(0)
	s_waitcnt lgkmcnt(0)
	s_barrier
	ds_read_b128 v[136:139], v154
	ds_read_b128 v[140:143], v155
	ds_read_b128 v[160:163], v155 offset:2048
	ds_read_b128 v[164:167], v154 offset:2048
	ds_read_b128 v[168:171], v154 offset:4096
	ds_read_b128 v[172:175], v154 offset:6144
	s_waitcnt lgkmcnt(3)
	s_setprio 1
	v_mfma_f32_32x32x16_bf16 v[114:129], v[136:139], v[140:143], v[114:129]
	v_mfma_f32_32x32x16_bf16 v[98:113], v[136:139], v[160:163], v[98:113]
	s_waitcnt lgkmcnt(2)
	v_mfma_f32_32x32x16_bf16 v[82:97], v[164:167], v[140:143], v[82:97]
	v_mfma_f32_32x32x16_bf16 v[66:81], v[164:167], v[160:163], v[66:81]
	s_waitcnt lgkmcnt(1)
	v_mfma_f32_32x32x16_bf16 v[50:65], v[168:171], v[140:143], v[50:65]
	v_mfma_f32_32x32x16_bf16 v[34:49], v[168:171], v[160:163], v[34:49]
	s_waitcnt lgkmcnt(0)
	v_mfma_f32_32x32x16_bf16 v[18:33], v[172:175], v[140:143], v[18:33]
	v_mfma_f32_32x32x16_bf16 v[2:17], v[172:175], v[160:163], v[2:17]
	s_setprio 0
	ds_read_b128 v[136:139], v156
	ds_read_b128 v[140:143], v157
	ds_read_b128 v[160:163], v157 offset:2048
	ds_read_b128 v[164:167], v156 offset:2048
	ds_read_b128 v[168:171], v156 offset:4096
	ds_read_b128 v[172:175], v156 offset:6144
	s_waitcnt lgkmcnt(3)
	s_setprio 1
	v_mfma_f32_32x32x16_bf16 v[114:129], v[136:139], v[140:143], v[114:129]
	v_mfma_f32_32x32x16_bf16 v[98:113], v[136:139], v[160:163], v[98:113]
	s_waitcnt lgkmcnt(2)
	v_mfma_f32_32x32x16_bf16 v[82:97], v[164:167], v[140:143], v[82:97]
	v_mfma_f32_32x32x16_bf16 v[66:81], v[164:167], v[160:163], v[66:81]
	s_waitcnt lgkmcnt(1)
	v_mfma_f32_32x32x16_bf16 v[50:65], v[168:171], v[140:143], v[50:65]
	v_mfma_f32_32x32x16_bf16 v[34:49], v[168:171], v[160:163], v[34:49]
	s_waitcnt lgkmcnt(0)
	v_mfma_f32_32x32x16_bf16 v[18:33], v[172:175], v[140:143], v[18:33]
	v_mfma_f32_32x32x16_bf16 v[2:17], v[172:175], v[160:163], v[2:17]
	s_setprio 0
	v_add_u32_e32 v138, s29, v151
	v_or_b32_e32 v136, s31, v150
	v_ashrrev_i32_e32 v139, 31, v138
	v_lshlrev_b64 v[142:143], 10, v[138:139]
	v_ashrrev_i32_e32 v137, 31, v136
	v_lshl_add_u64 v[142:143], v[142:143], 0, v[136:137]
	s_ashr_i32 s0, s28, 4
	v_lshlrev_b64 v[160:161], 2, v[142:143]
	s_add_i32 s0, s0, s10
	v_lshl_add_u64 v[142:143], s[98:99], 0, v[160:161]
	s_movk_i32 s29, 0x2000
	s_mul_hi_i32 s1, s0, 0x3000
	s_mulk_i32 s0, 0x3000
	v_add_co_u32_e32 v162, vcc, s29, v142
	s_add_u32 s0, s4, s0
	s_nop 0
	v_addc_co_u32_e32 v163, vcc, 0, v143, vcc
	s_addc_u32 s1, s5, s1
	v_add_co_u32_e32 v164, vcc, s73, v142
	s_add_u32 s0, s0, 0x2000
	s_nop 0
	v_addc_co_u32_e32 v165, vcc, 0, v143, vcc
	s_addc_u32 s1, s1, 0
	v_add_co_u32_e32 v166, vcc, s75, v142
	v_lshl_add_u64 v[140:141], v[136:137], 2, s[0:1]
	s_nop 0
	v_addc_co_u32_e32 v167, vcc, 0, v143, vcc
	s_waitcnt vmcnt(0) lgkmcnt(0)
	s_barrier
	v_and_b32_e32 v195, 63, v200
	v_lshrrev_b32_e32 v193, 5, v195
	v_and_b32_e32 v130, 31, v195
	v_lshlrev_b32_e32 v131, 2, v193
	v_sub_u32_e32 v138, v138, v131
	v_sub_u32_e32 v136, v136, v130
	v_lshrrev_b32_e32 v131, 6, v200
	v_mul_u32_u24_e32 v131, 0x2200, v131
	v_lshlrev_b32_e32 v130, 2, v130
	s_movk_i32 s28, 0x440
	v_mad_u32_u24 v130, v193, s28, v130
	v_add_u32_e32 v130, v130, v131
	v_lshrrev_b32_e32 v193, 4, v195
	v_and_b32_e32 v192, 15, v195
	s_movk_i32 s28, 0x110
	v_mad_u32_u24 v131, v193, s28, v131
	v_lshl_add_u32 v131, v192, 4, v131
	v_lshrrev_b32_e32 v194, 6, v136
	v_add_u32_e32 v138, v138, v193
	v_lshl_add_u32 v194, v138, 4, v194
	v_lshlrev_b32_e32 v194, 2, v194
	v_lshl_add_u32 v136, v192, 2, v136
	v_lshlrev_b32_e32 v195, 2, v136
	global_load_dwordx4 v[180:183], v195, s[0:1]
	v_lshl_add_u32 v0, v138, 10, v136
	v_lshlrev_b32_e32 v0, 2, v0
	s_mov_b64 s[36:37], s[98:99]
	s_mov_b64 s[38:39], s[56:57]
	v_readlane_b32 s28, v243, 5
	v_readlane_b32 s29, v243, 6
	global_load_dwordx4 v[148:151], v0, s[36:37] nt
	s_add_u32 s36, s36, 0x4000
	s_addc_u32 s37, s37, 0
	global_load_dwordx4 v[152:155], v0, s[36:37] nt
	s_add_u32 s36, s36, 0x4000
	s_addc_u32 s37, s37, 0
	global_load_dwordx4 v[156:159], v0, s[36:37] nt
	s_add_u32 s36, s36, 0x4000
	s_addc_u32 s37, s37, 0
	global_load_dwordx4 v[160:163], v0, s[36:37] nt
	s_add_u32 s36, s36, 0x4000
	s_addc_u32 s37, s37, 0
	global_load_dwordx4 v[164:167], v0, s[36:37] nt
	s_add_u32 s36, s36, 0x4000
	s_addc_u32 s37, s37, 0
	global_load_dwordx4 v[168:171], v0, s[36:37] nt
	s_add_u32 s36, s36, 0x4000
	s_addc_u32 s37, s37, 0
	global_load_dwordx4 v[172:175], v0, s[36:37] nt
	s_add_u32 s36, s36, 0x4000
	s_addc_u32 s37, s37, 0
	global_load_dwordx4 v[176:179], v0, s[36:37] nt
	s_add_u32 s36, s36, 0x4000
	s_addc_u32 s37, s37, 0
	ds_write2_b32 v130, v114, v98 offset0:0 offset1:32
	ds_write2_b32 v130, v115, v99 offset0:68 offset1:100
	ds_write2_b32 v130, v116, v100 offset0:136 offset1:168
	ds_write2_b32 v130, v117, v101 offset0:204 offset1:236
	v_add_u32_e32 v130, 0x880, v130
	ds_write2_b32 v130, v118, v102 offset0:0 offset1:32
	ds_write2_b32 v130, v119, v103 offset0:68 offset1:100
	ds_write2_b32 v130, v120, v104 offset0:136 offset1:168
	ds_write2_b32 v130, v121, v105 offset0:204 offset1:236
	v_add_u32_e32 v130, 0x880, v130
	ds_write2_b32 v130, v122, v106 offset0:0 offset1:32
	ds_write2_b32 v130, v123, v107 offset0:68 offset1:100
	ds_write2_b32 v130, v124, v108 offset0:136 offset1:168
	ds_write2_b32 v130, v125, v109 offset0:204 offset1:236
	v_add_u32_e32 v130, 0x880, v130
	ds_write2_b32 v130, v126, v110 offset0:0 offset1:32
	ds_write2_b32 v130, v127, v111 offset0:68 offset1:100
	ds_write2_b32 v130, v128, v112 offset0:136 offset1:168
	ds_write2_b32 v130, v129, v113 offset0:204 offset1:236
	v_subrev_u32_e32 v130, 0x1980, v130
	s_waitcnt lgkmcnt(0)
	ds_read_b128 v[98:101], v131
	ds_read_b128 v[102:105], v131 offset:1088
	ds_read_b128 v[106:109], v131 offset:2176
	ds_read_b128 v[110:113], v131 offset:3264
	ds_read_b128 v[114:117], v131 offset:4352
	ds_read_b128 v[118:121], v131 offset:5440
	ds_read_b128 v[122:125], v131 offset:6528
	ds_read_b128 v[126:129], v131 offset:7616
	s_waitcnt vmcnt(0) lgkmcnt(0)
	v_fma_f32 v98, v98, v180, v148
	v_fma_f32 v99, v99, v181, v149
	v_fma_f32 v100, v100, v182, v150
	v_fma_f32 v101, v101, v183, v151
	global_store_dwordx4 v0, v[98:101], s[38:39] nt
	s_add_u32 s38, s38, 0x4000
	s_addc_u32 s39, s39, 0
	v_mul_f32_e32 v184, v98, v98
	v_fmac_f32_e32 v184, v99, v99
	v_fmac_f32_e32 v184, v100, v100
	v_fmac_f32_e32 v184, v101, v101
	v_fma_f32 v102, v102, v180, v152
	v_fma_f32 v103, v103, v181, v153
	v_fma_f32 v104, v104, v182, v154
	v_fma_f32 v105, v105, v183, v155
	global_store_dwordx4 v0, v[102:105], s[38:39] nt
	s_add_u32 s38, s38, 0x4000
	s_addc_u32 s39, s39, 0
	v_mul_f32_e32 v185, v102, v102
	v_fmac_f32_e32 v185, v103, v103
	v_fmac_f32_e32 v185, v104, v104
	v_fmac_f32_e32 v185, v105, v105
	v_fma_f32 v106, v106, v180, v156
	v_fma_f32 v107, v107, v181, v157
	v_fma_f32 v108, v108, v182, v158
	v_fma_f32 v109, v109, v183, v159
	global_store_dwordx4 v0, v[106:109], s[38:39] nt
	s_add_u32 s38, s38, 0x4000
	s_addc_u32 s39, s39, 0
	v_mul_f32_e32 v186, v106, v106
	v_fmac_f32_e32 v186, v107, v107
	v_fmac_f32_e32 v186, v108, v108
	v_fmac_f32_e32 v186, v109, v109
	v_fma_f32 v110, v110, v180, v160
	v_fma_f32 v111, v111, v181, v161
	v_fma_f32 v112, v112, v182, v162
	v_fma_f32 v113, v113, v183, v163
	global_store_dwordx4 v0, v[110:113], s[38:39] nt
	s_add_u32 s38, s38, 0x4000
	s_addc_u32 s39, s39, 0
	v_mul_f32_e32 v187, v110, v110
	v_fmac_f32_e32 v187, v111, v111
	v_fmac_f32_e32 v187, v112, v112
	v_fmac_f32_e32 v187, v113, v113
	v_fma_f32 v114, v114, v180, v164
	v_fma_f32 v115, v115, v181, v165
	v_fma_f32 v116, v116, v182, v166
	v_fma_f32 v117, v117, v183, v167
	global_store_dwordx4 v0, v[114:117], s[38:39] nt
	s_add_u32 s38, s38, 0x4000
	s_addc_u32 s39, s39, 0
	v_mul_f32_e32 v188, v114, v114
	v_fmac_f32_e32 v188, v115, v115
	v_fmac_f32_e32 v188, v116, v116
	v_fmac_f32_e32 v188, v117, v117
	v_fma_f32 v118, v118, v180, v168
	v_fma_f32 v119, v119, v181, v169
	v_fma_f32 v120, v120, v182, v170
	v_fma_f32 v121, v121, v183, v171
	global_store_dwordx4 v0, v[118:121], s[38:39] nt
	s_add_u32 s38, s38, 0x4000
	s_addc_u32 s39, s39, 0
	v_mul_f32_e32 v189, v118, v118
	v_fmac_f32_e32 v189, v119, v119
	v_fmac_f32_e32 v189, v120, v120
	v_fmac_f32_e32 v189, v121, v121
	v_fma_f32 v122, v122, v180, v172
	v_fma_f32 v123, v123, v181, v173
	v_fma_f32 v124, v124, v182, v174
	v_fma_f32 v125, v125, v183, v175
	global_store_dwordx4 v0, v[122:125], s[38:39] nt
	s_add_u32 s38, s38, 0x4000
	s_addc_u32 s39, s39, 0
	v_mul_f32_e32 v190, v122, v122
	v_fmac_f32_e32 v190, v123, v123
	v_fmac_f32_e32 v190, v124, v124
	v_fmac_f32_e32 v190, v125, v125
	v_fma_f32 v126, v126, v180, v176
	v_fma_f32 v127, v127, v181, v177
	v_fma_f32 v128, v128, v182, v178
	v_fma_f32 v129, v129, v183, v179
	global_store_dwordx4 v0, v[126:129], s[38:39] nt
	s_add_u32 s38, s38, 0x4000
	s_addc_u32 s39, s39, 0
	v_mul_f32_e32 v191, v126, v126
	v_fmac_f32_e32 v191, v127, v127
	v_fmac_f32_e32 v191, v128, v128
	v_fmac_f32_e32 v191, v129, v129
	global_load_dwordx4 v[148:151], v0, s[36:37] nt
	s_add_u32 s36, s36, 0x4000
	s_addc_u32 s37, s37, 0
	global_load_dwordx4 v[152:155], v0, s[36:37] nt
	s_add_u32 s36, s36, 0x4000
	s_addc_u32 s37, s37, 0
	global_load_dwordx4 v[156:159], v0, s[36:37] nt
	s_add_u32 s36, s36, 0x4000
	s_addc_u32 s37, s37, 0
	global_load_dwordx4 v[160:163], v0, s[36:37] nt
	s_add_u32 s36, s36, 0x4000
	s_addc_u32 s37, s37, 0
	global_load_dwordx4 v[164:167], v0, s[36:37] nt
	s_add_u32 s36, s36, 0x4000
	s_addc_u32 s37, s37, 0
	global_load_dwordx4 v[168:171], v0, s[36:37] nt
	s_add_u32 s36, s36, 0x4000
	s_addc_u32 s37, s37, 0
	global_load_dwordx4 v[172:175], v0, s[36:37] nt
	s_add_u32 s36, s36, 0x4000
	s_addc_u32 s37, s37, 0
	global_load_dwordx4 v[176:179], v0, s[36:37] nt
	s_add_u32 s36, s36, 0x4000
	s_addc_u32 s37, s37, 0
	v_add_f32_dpp v184, v184, v184 quad_perm:[1,0,3,2] row_mask:0xf bank_mask:0xf
	v_add_f32_dpp v185, v185, v185 quad_perm:[1,0,3,2] row_mask:0xf bank_mask:0xf
	v_add_f32_dpp v186, v186, v186 quad_perm:[1,0,3,2] row_mask:0xf bank_mask:0xf
	v_add_f32_dpp v187, v187, v187 quad_perm:[1,0,3,2] row_mask:0xf bank_mask:0xf
	v_add_f32_dpp v188, v188, v188 quad_perm:[1,0,3,2] row_mask:0xf bank_mask:0xf
	v_add_f32_dpp v189, v189, v189 quad_perm:[1,0,3,2] row_mask:0xf bank_mask:0xf
	v_add_f32_dpp v190, v190, v190 quad_perm:[1,0,3,2] row_mask:0xf bank_mask:0xf
	v_add_f32_dpp v191, v191, v191 quad_perm:[1,0,3,2] row_mask:0xf bank_mask:0xf
	v_add_f32_dpp v184, v184, v184 quad_perm:[2,3,0,1] row_mask:0xf bank_mask:0xf
	v_add_f32_dpp v185, v185, v185 quad_perm:[2,3,0,1] row_mask:0xf bank_mask:0xf
	v_add_f32_dpp v186, v186, v186 quad_perm:[2,3,0,1] row_mask:0xf bank_mask:0xf
	v_add_f32_dpp v187, v187, v187 quad_perm:[2,3,0,1] row_mask:0xf bank_mask:0xf
	v_add_f32_dpp v188, v188, v188 quad_perm:[2,3,0,1] row_mask:0xf bank_mask:0xf
	v_add_f32_dpp v189, v189, v189 quad_perm:[2,3,0,1] row_mask:0xf bank_mask:0xf
	v_add_f32_dpp v190, v190, v190 quad_perm:[2,3,0,1] row_mask:0xf bank_mask:0xf
	v_add_f32_dpp v191, v191, v191 quad_perm:[2,3,0,1] row_mask:0xf bank_mask:0xf
	v_add_f32_dpp v184, v184, v184 row_half_mirror row_mask:0xf bank_mask:0xf
	v_add_f32_dpp v185, v185, v185 row_half_mirror row_mask:0xf bank_mask:0xf
	v_add_f32_dpp v186, v186, v186 row_half_mirror row_mask:0xf bank_mask:0xf
	v_add_f32_dpp v187, v187, v187 row_half_mirror row_mask:0xf bank_mask:0xf
	v_add_f32_dpp v188, v188, v188 row_half_mirror row_mask:0xf bank_mask:0xf
	v_add_f32_dpp v189, v189, v189 row_half_mirror row_mask:0xf bank_mask:0xf
	v_add_f32_dpp v190, v190, v190 row_half_mirror row_mask:0xf bank_mask:0xf
	v_add_f32_dpp v191, v191, v191 row_half_mirror row_mask:0xf bank_mask:0xf
	v_add_f32_dpp v184, v184, v184 row_mirror row_mask:0xf bank_mask:0xf
	v_add_f32_dpp v185, v185, v185 row_mirror row_mask:0xf bank_mask:0xf
	v_add_f32_dpp v186, v186, v186 row_mirror row_mask:0xf bank_mask:0xf
	v_add_f32_dpp v187, v187, v187 row_mirror row_mask:0xf bank_mask:0xf
	v_add_f32_dpp v188, v188, v188 row_mirror row_mask:0xf bank_mask:0xf
	v_add_f32_dpp v189, v189, v189 row_mirror row_mask:0xf bank_mask:0xf
	v_add_f32_dpp v190, v190, v190 row_mirror row_mask:0xf bank_mask:0xf
	v_add_f32_dpp v191, v191, v191 row_mirror row_mask:0xf bank_mask:0xf
	v_cmp_eq_u32_e32 vcc, 0, v192
	s_and_saveexec_b64 s[0:1], vcc
	global_store_dword v194, v184, s[28:29]
	s_add_u32 s28, s28, 0x100
	s_addc_u32 s29, s29, 0
	global_store_dword v194, v185, s[28:29]
	s_add_u32 s28, s28, 0x100
	s_addc_u32 s29, s29, 0
	global_store_dword v194, v186, s[28:29]
	s_add_u32 s28, s28, 0x100
	s_addc_u32 s29, s29, 0
	global_store_dword v194, v187, s[28:29]
	s_add_u32 s28, s28, 0x100
	s_addc_u32 s29, s29, 0
	global_store_dword v194, v188, s[28:29]
	s_add_u32 s28, s28, 0x100
	s_addc_u32 s29, s29, 0
	global_store_dword v194, v189, s[28:29]
	s_add_u32 s28, s28, 0x100
	s_addc_u32 s29, s29, 0
	global_store_dword v194, v190, s[28:29]
	s_add_u32 s28, s28, 0x100
	s_addc_u32 s29, s29, 0
	global_store_dword v194, v191, s[28:29]
	s_add_u32 s28, s28, 0x100
	s_addc_u32 s29, s29, 0
	s_or_b64 exec, exec, s[0:1]
	ds_write2_b32 v130, v82, v66 offset0:0 offset1:32
	ds_write2_b32 v130, v83, v67 offset0:68 offset1:100
	ds_write2_b32 v130, v84, v68 offset0:136 offset1:168
	ds_write2_b32 v130, v85, v69 offset0:204 offset1:236
	v_add_u32_e32 v130, 0x880, v130
	ds_write2_b32 v130, v86, v70 offset0:0 offset1:32
	ds_write2_b32 v130, v87, v71 offset0:68 offset1:100
	ds_write2_b32 v130, v88, v72 offset0:136 offset1:168
	ds_write2_b32 v130, v89, v73 offset0:204 offset1:236
	v_add_u32_e32 v130, 0x880, v130
	ds_write2_b32 v130, v90, v74 offset0:0 offset1:32
	ds_write2_b32 v130, v91, v75 offset0:68 offset1:100
	ds_write2_b32 v130, v92, v76 offset0:136 offset1:168
	ds_write2_b32 v130, v93, v77 offset0:204 offset1:236
	v_add_u32_e32 v130, 0x880, v130
	ds_write2_b32 v130, v94, v78 offset0:0 offset1:32
	ds_write2_b32 v130, v95, v79 offset0:68 offset1:100
	ds_write2_b32 v130, v96, v80 offset0:136 offset1:168
	ds_write2_b32 v130, v97, v81 offset0:204 offset1:236
	v_subrev_u32_e32 v130, 0x1980, v130
	s_waitcnt lgkmcnt(0)
	ds_read_b128 v[66:69], v131
	ds_read_b128 v[70:73], v131 offset:1088
	ds_read_b128 v[74:77], v131 offset:2176
	ds_read_b128 v[78:81], v131 offset:3264
	ds_read_b128 v[82:85], v131 offset:4352
	ds_read_b128 v[86:89], v131 offset:5440
	ds_read_b128 v[90:93], v131 offset:6528
	ds_read_b128 v[94:97], v131 offset:7616
	s_waitcnt vmcnt(8) lgkmcnt(0)
	v_fma_f32 v66, v66, v180, v148
	v_fma_f32 v67, v67, v181, v149
	v_fma_f32 v68, v68, v182, v150
	v_fma_f32 v69, v69, v183, v151
	global_store_dwordx4 v0, v[66:69], s[38:39] nt
	s_add_u32 s38, s38, 0x4000
	s_addc_u32 s39, s39, 0
	v_mul_f32_e32 v184, v66, v66
	v_fmac_f32_e32 v184, v67, v67
	v_fmac_f32_e32 v184, v68, v68
	v_fmac_f32_e32 v184, v69, v69
	v_fma_f32 v70, v70, v180, v152
	v_fma_f32 v71, v71, v181, v153
	v_fma_f32 v72, v72, v182, v154
	v_fma_f32 v73, v73, v183, v155
	global_store_dwordx4 v0, v[70:73], s[38:39] nt
	s_add_u32 s38, s38, 0x4000
	s_addc_u32 s39, s39, 0
	v_mul_f32_e32 v185, v70, v70
	v_fmac_f32_e32 v185, v71, v71
	v_fmac_f32_e32 v185, v72, v72
	v_fmac_f32_e32 v185, v73, v73
	v_fma_f32 v74, v74, v180, v156
	v_fma_f32 v75, v75, v181, v157
	v_fma_f32 v76, v76, v182, v158
	v_fma_f32 v77, v77, v183, v159
	global_store_dwordx4 v0, v[74:77], s[38:39] nt
	s_add_u32 s38, s38, 0x4000
	s_addc_u32 s39, s39, 0
	v_mul_f32_e32 v186, v74, v74
	v_fmac_f32_e32 v186, v75, v75
	v_fmac_f32_e32 v186, v76, v76
	v_fmac_f32_e32 v186, v77, v77
	v_fma_f32 v78, v78, v180, v160
	v_fma_f32 v79, v79, v181, v161
	v_fma_f32 v80, v80, v182, v162
	v_fma_f32 v81, v81, v183, v163
	global_store_dwordx4 v0, v[78:81], s[38:39] nt
	s_add_u32 s38, s38, 0x4000
	s_addc_u32 s39, s39, 0
	v_mul_f32_e32 v187, v78, v78
	v_fmac_f32_e32 v187, v79, v79
	v_fmac_f32_e32 v187, v80, v80
	v_fmac_f32_e32 v187, v81, v81
	v_fma_f32 v82, v82, v180, v164
	v_fma_f32 v83, v83, v181, v165
	v_fma_f32 v84, v84, v182, v166
	v_fma_f32 v85, v85, v183, v167
	global_store_dwordx4 v0, v[82:85], s[38:39] nt
	s_add_u32 s38, s38, 0x4000
	s_addc_u32 s39, s39, 0
	v_mul_f32_e32 v188, v82, v82
	v_fmac_f32_e32 v188, v83, v83
	v_fmac_f32_e32 v188, v84, v84
	v_fmac_f32_e32 v188, v85, v85
	v_fma_f32 v86, v86, v180, v168
	v_fma_f32 v87, v87, v181, v169
	v_fma_f32 v88, v88, v182, v170
	v_fma_f32 v89, v89, v183, v171
	global_store_dwordx4 v0, v[86:89], s[38:39] nt
	s_add_u32 s38, s38, 0x4000
	s_addc_u32 s39, s39, 0
	v_mul_f32_e32 v189, v86, v86
	v_fmac_f32_e32 v189, v87, v87
	v_fmac_f32_e32 v189, v88, v88
	v_fmac_f32_e32 v189, v89, v89
	v_fma_f32 v90, v90, v180, v172
	v_fma_f32 v91, v91, v181, v173
	v_fma_f32 v92, v92, v182, v174
	v_fma_f32 v93, v93, v183, v175
	global_store_dwordx4 v0, v[90:93], s[38:39] nt
	s_add_u32 s38, s38, 0x4000
	s_addc_u32 s39, s39, 0
	v_mul_f32_e32 v190, v90, v90
	v_fmac_f32_e32 v190, v91, v91
	v_fmac_f32_e32 v190, v92, v92
	v_fmac_f32_e32 v190, v93, v93
	v_fma_f32 v94, v94, v180, v176
	v_fma_f32 v95, v95, v181, v177
	v_fma_f32 v96, v96, v182, v178
	v_fma_f32 v97, v97, v183, v179
	global_store_dwordx4 v0, v[94:97], s[38:39] nt
	s_add_u32 s38, s38, 0x4000
	s_addc_u32 s39, s39, 0
	v_mul_f32_e32 v191, v94, v94
	v_fmac_f32_e32 v191, v95, v95
	v_fmac_f32_e32 v191, v96, v96
	v_fmac_f32_e32 v191, v97, v97
	global_load_dwordx4 v[148:151], v0, s[36:37] nt
	s_add_u32 s36, s36, 0x4000
	s_addc_u32 s37, s37, 0
	global_load_dwordx4 v[152:155], v0, s[36:37] nt
	s_add_u32 s36, s36, 0x4000
	s_addc_u32 s37, s37, 0
	global_load_dwordx4 v[156:159], v0, s[36:37] nt
	s_add_u32 s36, s36, 0x4000
	s_addc_u32 s37, s37, 0
	global_load_dwordx4 v[160:163], v0, s[36:37] nt
	s_add_u32 s36, s36, 0x4000
	s_addc_u32 s37, s37, 0
	global_load_dwordx4 v[164:167], v0, s[36:37] nt
	s_add_u32 s36, s36, 0x4000
	s_addc_u32 s37, s37, 0
	global_load_dwordx4 v[168:171], v0, s[36:37] nt
	s_add_u32 s36, s36, 0x4000
	s_addc_u32 s37, s37, 0
	global_load_dwordx4 v[172:175], v0, s[36:37] nt
	s_add_u32 s36, s36, 0x4000
	s_addc_u32 s37, s37, 0
	global_load_dwordx4 v[176:179], v0, s[36:37] nt
	s_add_u32 s36, s36, 0x4000
	s_addc_u32 s37, s37, 0
	v_add_f32_dpp v184, v184, v184 quad_perm:[1,0,3,2] row_mask:0xf bank_mask:0xf
	v_add_f32_dpp v185, v185, v185 quad_perm:[1,0,3,2] row_mask:0xf bank_mask:0xf
	v_add_f32_dpp v186, v186, v186 quad_perm:[1,0,3,2] row_mask:0xf bank_mask:0xf
	v_add_f32_dpp v187, v187, v187 quad_perm:[1,0,3,2] row_mask:0xf bank_mask:0xf
	v_add_f32_dpp v188, v188, v188 quad_perm:[1,0,3,2] row_mask:0xf bank_mask:0xf
	v_add_f32_dpp v189, v189, v189 quad_perm:[1,0,3,2] row_mask:0xf bank_mask:0xf
	v_add_f32_dpp v190, v190, v190 quad_perm:[1,0,3,2] row_mask:0xf bank_mask:0xf
	v_add_f32_dpp v191, v191, v191 quad_perm:[1,0,3,2] row_mask:0xf bank_mask:0xf
	v_add_f32_dpp v184, v184, v184 quad_perm:[2,3,0,1] row_mask:0xf bank_mask:0xf
	v_add_f32_dpp v185, v185, v185 quad_perm:[2,3,0,1] row_mask:0xf bank_mask:0xf
	v_add_f32_dpp v186, v186, v186 quad_perm:[2,3,0,1] row_mask:0xf bank_mask:0xf
	v_add_f32_dpp v187, v187, v187 quad_perm:[2,3,0,1] row_mask:0xf bank_mask:0xf
	v_add_f32_dpp v188, v188, v188 quad_perm:[2,3,0,1] row_mask:0xf bank_mask:0xf
	v_add_f32_dpp v189, v189, v189 quad_perm:[2,3,0,1] row_mask:0xf bank_mask:0xf
	v_add_f32_dpp v190, v190, v190 quad_perm:[2,3,0,1] row_mask:0xf bank_mask:0xf
	v_add_f32_dpp v191, v191, v191 quad_perm:[2,3,0,1] row_mask:0xf bank_mask:0xf
	v_add_f32_dpp v184, v184, v184 row_half_mirror row_mask:0xf bank_mask:0xf
	v_add_f32_dpp v185, v185, v185 row_half_mirror row_mask:0xf bank_mask:0xf
	v_add_f32_dpp v186, v186, v186 row_half_mirror row_mask:0xf bank_mask:0xf
	v_add_f32_dpp v187, v187, v187 row_half_mirror row_mask:0xf bank_mask:0xf
	v_add_f32_dpp v188, v188, v188 row_half_mirror row_mask:0xf bank_mask:0xf
	v_add_f32_dpp v189, v189, v189 row_half_mirror row_mask:0xf bank_mask:0xf
	v_add_f32_dpp v190, v190, v190 row_half_mirror row_mask:0xf bank_mask:0xf
	v_add_f32_dpp v191, v191, v191 row_half_mirror row_mask:0xf bank_mask:0xf
	v_add_f32_dpp v184, v184, v184 row_mirror row_mask:0xf bank_mask:0xf
	v_add_f32_dpp v185, v185, v185 row_mirror row_mask:0xf bank_mask:0xf
	v_add_f32_dpp v186, v186, v186 row_mirror row_mask:0xf bank_mask:0xf
	v_add_f32_dpp v187, v187, v187 row_mirror row_mask:0xf bank_mask:0xf
	v_add_f32_dpp v188, v188, v188 row_mirror row_mask:0xf bank_mask:0xf
	v_add_f32_dpp v189, v189, v189 row_mirror row_mask:0xf bank_mask:0xf
	v_add_f32_dpp v190, v190, v190 row_mirror row_mask:0xf bank_mask:0xf
	v_add_f32_dpp v191, v191, v191 row_mirror row_mask:0xf bank_mask:0xf
	v_cmp_eq_u32_e32 vcc, 0, v192
	s_and_saveexec_b64 s[0:1], vcc
	global_store_dword v194, v184, s[28:29]
	s_add_u32 s28, s28, 0x100
	s_addc_u32 s29, s29, 0
	global_store_dword v194, v185, s[28:29]
	s_add_u32 s28, s28, 0x100
	s_addc_u32 s29, s29, 0
	global_store_dword v194, v186, s[28:29]
	s_add_u32 s28, s28, 0x100
	s_addc_u32 s29, s29, 0
	global_store_dword v194, v187, s[28:29]
	s_add_u32 s28, s28, 0x100
	s_addc_u32 s29, s29, 0
	global_store_dword v194, v188, s[28:29]
	s_add_u32 s28, s28, 0x100
	s_addc_u32 s29, s29, 0
	global_store_dword v194, v189, s[28:29]
	s_add_u32 s28, s28, 0x100
	s_addc_u32 s29, s29, 0
	global_store_dword v194, v190, s[28:29]
	s_add_u32 s28, s28, 0x100
	s_addc_u32 s29, s29, 0
	global_store_dword v194, v191, s[28:29]
	s_add_u32 s28, s28, 0x100
	s_addc_u32 s29, s29, 0
	s_or_b64 exec, exec, s[0:1]
	ds_write2_b32 v130, v50, v34 offset0:0 offset1:32
	ds_write2_b32 v130, v51, v35 offset0:68 offset1:100
	ds_write2_b32 v130, v52, v36 offset0:136 offset1:168
	ds_write2_b32 v130, v53, v37 offset0:204 offset1:236
	v_add_u32_e32 v130, 0x880, v130
	ds_write2_b32 v130, v54, v38 offset0:0 offset1:32
	ds_write2_b32 v130, v55, v39 offset0:68 offset1:100
	ds_write2_b32 v130, v56, v40 offset0:136 offset1:168
	ds_write2_b32 v130, v57, v41 offset0:204 offset1:236
	v_add_u32_e32 v130, 0x880, v130
	ds_write2_b32 v130, v58, v42 offset0:0 offset1:32
	ds_write2_b32 v130, v59, v43 offset0:68 offset1:100
	ds_write2_b32 v130, v60, v44 offset0:136 offset1:168
	ds_write2_b32 v130, v61, v45 offset0:204 offset1:236
	v_add_u32_e32 v130, 0x880, v130
	ds_write2_b32 v130, v62, v46 offset0:0 offset1:32
	ds_write2_b32 v130, v63, v47 offset0:68 offset1:100
	ds_write2_b32 v130, v64, v48 offset0:136 offset1:168
	ds_write2_b32 v130, v65, v49 offset0:204 offset1:236
	v_subrev_u32_e32 v130, 0x1980, v130
	s_waitcnt lgkmcnt(0)
	ds_read_b128 v[34:37], v131
	ds_read_b128 v[38:41], v131 offset:1088
	ds_read_b128 v[42:45], v131 offset:2176
	ds_read_b128 v[46:49], v131 offset:3264
	ds_read_b128 v[50:53], v131 offset:4352
	ds_read_b128 v[54:57], v131 offset:5440
	ds_read_b128 v[58:61], v131 offset:6528
	ds_read_b128 v[62:65], v131 offset:7616
	s_waitcnt vmcnt(8) lgkmcnt(0)
	v_fma_f32 v34, v34, v180, v148
	v_fma_f32 v35, v35, v181, v149
	v_fma_f32 v36, v36, v182, v150
	v_fma_f32 v37, v37, v183, v151
	global_store_dwordx4 v0, v[34:37], s[38:39] nt
	s_add_u32 s38, s38, 0x4000
	s_addc_u32 s39, s39, 0
	v_mul_f32_e32 v184, v34, v34
	v_fmac_f32_e32 v184, v35, v35
	v_fmac_f32_e32 v184, v36, v36
	v_fmac_f32_e32 v184, v37, v37
	v_fma_f32 v38, v38, v180, v152
	v_fma_f32 v39, v39, v181, v153
	v_fma_f32 v40, v40, v182, v154
	v_fma_f32 v41, v41, v183, v155
	global_store_dwordx4 v0, v[38:41], s[38:39] nt
	s_add_u32 s38, s38, 0x4000
	s_addc_u32 s39, s39, 0
	v_mul_f32_e32 v185, v38, v38
	v_fmac_f32_e32 v185, v39, v39
	v_fmac_f32_e32 v185, v40, v40
	v_fmac_f32_e32 v185, v41, v41
	v_fma_f32 v42, v42, v180, v156
	v_fma_f32 v43, v43, v181, v157
	v_fma_f32 v44, v44, v182, v158
	v_fma_f32 v45, v45, v183, v159
	global_store_dwordx4 v0, v[42:45], s[38:39] nt
	s_add_u32 s38, s38, 0x4000
	s_addc_u32 s39, s39, 0
	v_mul_f32_e32 v186, v42, v42
	v_fmac_f32_e32 v186, v43, v43
	v_fmac_f32_e32 v186, v44, v44
	v_fmac_f32_e32 v186, v45, v45
	v_fma_f32 v46, v46, v180, v160
	v_fma_f32 v47, v47, v181, v161
	v_fma_f32 v48, v48, v182, v162
	v_fma_f32 v49, v49, v183, v163
	global_store_dwordx4 v0, v[46:49], s[38:39] nt
	s_add_u32 s38, s38, 0x4000
	s_addc_u32 s39, s39, 0
	v_mul_f32_e32 v187, v46, v46
	v_fmac_f32_e32 v187, v47, v47
	v_fmac_f32_e32 v187, v48, v48
	v_fmac_f32_e32 v187, v49, v49
	v_fma_f32 v50, v50, v180, v164
	v_fma_f32 v51, v51, v181, v165
	v_fma_f32 v52, v52, v182, v166
	v_fma_f32 v53, v53, v183, v167
	global_store_dwordx4 v0, v[50:53], s[38:39] nt
	s_add_u32 s38, s38, 0x4000
	s_addc_u32 s39, s39, 0
	v_mul_f32_e32 v188, v50, v50
	v_fmac_f32_e32 v188, v51, v51
	v_fmac_f32_e32 v188, v52, v52
	v_fmac_f32_e32 v188, v53, v53
	v_fma_f32 v54, v54, v180, v168
	v_fma_f32 v55, v55, v181, v169
	v_fma_f32 v56, v56, v182, v170
	v_fma_f32 v57, v57, v183, v171
	global_store_dwordx4 v0, v[54:57], s[38:39] nt
	s_add_u32 s38, s38, 0x4000
	s_addc_u32 s39, s39, 0
	v_mul_f32_e32 v189, v54, v54
	v_fmac_f32_e32 v189, v55, v55
	v_fmac_f32_e32 v189, v56, v56
	v_fmac_f32_e32 v189, v57, v57
	v_fma_f32 v58, v58, v180, v172
	v_fma_f32 v59, v59, v181, v173
	v_fma_f32 v60, v60, v182, v174
	v_fma_f32 v61, v61, v183, v175
	global_store_dwordx4 v0, v[58:61], s[38:39] nt
	s_add_u32 s38, s38, 0x4000
	s_addc_u32 s39, s39, 0
	v_mul_f32_e32 v190, v58, v58
	v_fmac_f32_e32 v190, v59, v59
	v_fmac_f32_e32 v190, v60, v60
	v_fmac_f32_e32 v190, v61, v61
	v_fma_f32 v62, v62, v180, v176
	v_fma_f32 v63, v63, v181, v177
	v_fma_f32 v64, v64, v182, v178
	v_fma_f32 v65, v65, v183, v179
	global_store_dwordx4 v0, v[62:65], s[38:39] nt
	s_add_u32 s38, s38, 0x4000
	s_addc_u32 s39, s39, 0
	v_mul_f32_e32 v191, v62, v62
	v_fmac_f32_e32 v191, v63, v63
	v_fmac_f32_e32 v191, v64, v64
	v_fmac_f32_e32 v191, v65, v65
	global_load_dwordx4 v[148:151], v0, s[36:37] nt
	s_add_u32 s36, s36, 0x4000
	s_addc_u32 s37, s37, 0
	global_load_dwordx4 v[152:155], v0, s[36:37] nt
	s_add_u32 s36, s36, 0x4000
	s_addc_u32 s37, s37, 0
	global_load_dwordx4 v[156:159], v0, s[36:37] nt
	s_add_u32 s36, s36, 0x4000
	s_addc_u32 s37, s37, 0
	global_load_dwordx4 v[160:163], v0, s[36:37] nt
	s_add_u32 s36, s36, 0x4000
	s_addc_u32 s37, s37, 0
	global_load_dwordx4 v[164:167], v0, s[36:37] nt
	s_add_u32 s36, s36, 0x4000
	s_addc_u32 s37, s37, 0
	global_load_dwordx4 v[168:171], v0, s[36:37] nt
	s_add_u32 s36, s36, 0x4000
	s_addc_u32 s37, s37, 0
	global_load_dwordx4 v[172:175], v0, s[36:37] nt
	s_add_u32 s36, s36, 0x4000
	s_addc_u32 s37, s37, 0
	global_load_dwordx4 v[176:179], v0, s[36:37] nt
	s_add_u32 s36, s36, 0x4000
	s_addc_u32 s37, s37, 0
	v_add_f32_dpp v184, v184, v184 quad_perm:[1,0,3,2] row_mask:0xf bank_mask:0xf
	v_add_f32_dpp v185, v185, v185 quad_perm:[1,0,3,2] row_mask:0xf bank_mask:0xf
	v_add_f32_dpp v186, v186, v186 quad_perm:[1,0,3,2] row_mask:0xf bank_mask:0xf
	v_add_f32_dpp v187, v187, v187 quad_perm:[1,0,3,2] row_mask:0xf bank_mask:0xf
	v_add_f32_dpp v188, v188, v188 quad_perm:[1,0,3,2] row_mask:0xf bank_mask:0xf
	v_add_f32_dpp v189, v189, v189 quad_perm:[1,0,3,2] row_mask:0xf bank_mask:0xf
	v_add_f32_dpp v190, v190, v190 quad_perm:[1,0,3,2] row_mask:0xf bank_mask:0xf
	v_add_f32_dpp v191, v191, v191 quad_perm:[1,0,3,2] row_mask:0xf bank_mask:0xf
	v_add_f32_dpp v184, v184, v184 quad_perm:[2,3,0,1] row_mask:0xf bank_mask:0xf
	v_add_f32_dpp v185, v185, v185 quad_perm:[2,3,0,1] row_mask:0xf bank_mask:0xf
	v_add_f32_dpp v186, v186, v186 quad_perm:[2,3,0,1] row_mask:0xf bank_mask:0xf
	v_add_f32_dpp v187, v187, v187 quad_perm:[2,3,0,1] row_mask:0xf bank_mask:0xf
	v_add_f32_dpp v188, v188, v188 quad_perm:[2,3,0,1] row_mask:0xf bank_mask:0xf
	v_add_f32_dpp v189, v189, v189 quad_perm:[2,3,0,1] row_mask:0xf bank_mask:0xf
	v_add_f32_dpp v190, v190, v190 quad_perm:[2,3,0,1] row_mask:0xf bank_mask:0xf
	v_add_f32_dpp v191, v191, v191 quad_perm:[2,3,0,1] row_mask:0xf bank_mask:0xf
	v_add_f32_dpp v184, v184, v184 row_half_mirror row_mask:0xf bank_mask:0xf
	v_add_f32_dpp v185, v185, v185 row_half_mirror row_mask:0xf bank_mask:0xf
	v_add_f32_dpp v186, v186, v186 row_half_mirror row_mask:0xf bank_mask:0xf
	v_add_f32_dpp v187, v187, v187 row_half_mirror row_mask:0xf bank_mask:0xf
	v_add_f32_dpp v188, v188, v188 row_half_mirror row_mask:0xf bank_mask:0xf
	v_add_f32_dpp v189, v189, v189 row_half_mirror row_mask:0xf bank_mask:0xf
	v_add_f32_dpp v190, v190, v190 row_half_mirror row_mask:0xf bank_mask:0xf
	v_add_f32_dpp v191, v191, v191 row_half_mirror row_mask:0xf bank_mask:0xf
	v_add_f32_dpp v184, v184, v184 row_mirror row_mask:0xf bank_mask:0xf
	v_add_f32_dpp v185, v185, v185 row_mirror row_mask:0xf bank_mask:0xf
	v_add_f32_dpp v186, v186, v186 row_mirror row_mask:0xf bank_mask:0xf
	v_add_f32_dpp v187, v187, v187 row_mirror row_mask:0xf bank_mask:0xf
	v_add_f32_dpp v188, v188, v188 row_mirror row_mask:0xf bank_mask:0xf
	v_add_f32_dpp v189, v189, v189 row_mirror row_mask:0xf bank_mask:0xf
	v_add_f32_dpp v190, v190, v190 row_mirror row_mask:0xf bank_mask:0xf
	v_add_f32_dpp v191, v191, v191 row_mirror row_mask:0xf bank_mask:0xf
	v_cmp_eq_u32_e32 vcc, 0, v192
	s_and_saveexec_b64 s[0:1], vcc
	global_store_dword v194, v184, s[28:29]
	s_add_u32 s28, s28, 0x100
	s_addc_u32 s29, s29, 0
	global_store_dword v194, v185, s[28:29]
	s_add_u32 s28, s28, 0x100
	s_addc_u32 s29, s29, 0
	global_store_dword v194, v186, s[28:29]
	s_add_u32 s28, s28, 0x100
	s_addc_u32 s29, s29, 0
	global_store_dword v194, v187, s[28:29]
	s_add_u32 s28, s28, 0x100
	s_addc_u32 s29, s29, 0
	global_store_dword v194, v188, s[28:29]
	s_add_u32 s28, s28, 0x100
	s_addc_u32 s29, s29, 0
	global_store_dword v194, v189, s[28:29]
	s_add_u32 s28, s28, 0x100
	s_addc_u32 s29, s29, 0
	global_store_dword v194, v190, s[28:29]
	s_add_u32 s28, s28, 0x100
	s_addc_u32 s29, s29, 0
	global_store_dword v194, v191, s[28:29]
	s_add_u32 s28, s28, 0x100
	s_addc_u32 s29, s29, 0
	s_or_b64 exec, exec, s[0:1]
	ds_write2_b32 v130, v18, v2 offset0:0 offset1:32
	ds_write2_b32 v130, v19, v3 offset0:68 offset1:100
	ds_write2_b32 v130, v20, v4 offset0:136 offset1:168
	ds_write2_b32 v130, v21, v5 offset0:204 offset1:236
	v_add_u32_e32 v130, 0x880, v130
	ds_write2_b32 v130, v22, v6 offset0:0 offset1:32
	ds_write2_b32 v130, v23, v7 offset0:68 offset1:100
	ds_write2_b32 v130, v24, v8 offset0:136 offset1:168
	ds_write2_b32 v130, v25, v9 offset0:204 offset1:236
	v_add_u32_e32 v130, 0x880, v130
	ds_write2_b32 v130, v26, v10 offset0:0 offset1:32
	ds_write2_b32 v130, v27, v11 offset0:68 offset1:100
	ds_write2_b32 v130, v28, v12 offset0:136 offset1:168
	ds_write2_b32 v130, v29, v13 offset0:204 offset1:236
	v_add_u32_e32 v130, 0x880, v130
	ds_write2_b32 v130, v30, v14 offset0:0 offset1:32
	ds_write2_b32 v130, v31, v15 offset0:68 offset1:100
	ds_write2_b32 v130, v32, v16 offset0:136 offset1:168
	ds_write2_b32 v130, v33, v17 offset0:204 offset1:236
	v_subrev_u32_e32 v130, 0x1980, v130
	s_waitcnt lgkmcnt(0)
	ds_read_b128 v[132:135], v131
	ds_read_b128 v[136:139], v131 offset:1088
	ds_read_b128 v[140:143], v131 offset:2176
	ds_read_b128 v[144:147], v131 offset:3264
	ds_read_b128 v[18:21], v131 offset:4352
	ds_read_b128 v[22:25], v131 offset:5440
	ds_read_b128 v[26:29], v131 offset:6528
	ds_read_b128 v[30:33], v131 offset:7616
	s_waitcnt vmcnt(8) lgkmcnt(0)
	v_fma_f32 v132, v132, v180, v148
	v_fma_f32 v133, v133, v181, v149
	v_fma_f32 v134, v134, v182, v150
	v_fma_f32 v135, v135, v183, v151
	global_store_dwordx4 v0, v[132:135], s[38:39] nt
	s_add_u32 s38, s38, 0x4000
	s_addc_u32 s39, s39, 0
	v_mul_f32_e32 v184, v132, v132
	v_fmac_f32_e32 v184, v133, v133
	v_fmac_f32_e32 v184, v134, v134
	v_fmac_f32_e32 v184, v135, v135
	v_fma_f32 v136, v136, v180, v152
	v_fma_f32 v137, v137, v181, v153
	v_fma_f32 v138, v138, v182, v154
	v_fma_f32 v139, v139, v183, v155
	global_store_dwordx4 v0, v[136:139], s[38:39] nt
	s_add_u32 s38, s38, 0x4000
	s_addc_u32 s39, s39, 0
	v_mul_f32_e32 v185, v136, v136
	v_fmac_f32_e32 v185, v137, v137
	v_fmac_f32_e32 v185, v138, v138
	v_fmac_f32_e32 v185, v139, v139
	v_fma_f32 v140, v140, v180, v156
	v_fma_f32 v141, v141, v181, v157
	v_fma_f32 v142, v142, v182, v158
	v_fma_f32 v143, v143, v183, v159
	global_store_dwordx4 v0, v[140:143], s[38:39] nt
	s_add_u32 s38, s38, 0x4000
	s_addc_u32 s39, s39, 0
	v_mul_f32_e32 v186, v140, v140
	v_fmac_f32_e32 v186, v141, v141
	v_fmac_f32_e32 v186, v142, v142
	v_fmac_f32_e32 v186, v143, v143
	v_fma_f32 v144, v144, v180, v160
	v_fma_f32 v145, v145, v181, v161
	v_fma_f32 v146, v146, v182, v162
	v_fma_f32 v147, v147, v183, v163
	global_store_dwordx4 v0, v[144:147], s[38:39] nt
	s_add_u32 s38, s38, 0x4000
	s_addc_u32 s39, s39, 0
	v_mul_f32_e32 v187, v144, v144
	v_fmac_f32_e32 v187, v145, v145
	v_fmac_f32_e32 v187, v146, v146
	v_fmac_f32_e32 v187, v147, v147
	v_fma_f32 v18, v18, v180, v164
	v_fma_f32 v19, v19, v181, v165
	v_fma_f32 v20, v20, v182, v166
	v_fma_f32 v21, v21, v183, v167
	global_store_dwordx4 v0, v[18:21], s[38:39] nt
	s_add_u32 s38, s38, 0x4000
	s_addc_u32 s39, s39, 0
	v_mul_f32_e32 v188, v18, v18
	v_fmac_f32_e32 v188, v19, v19
	v_fmac_f32_e32 v188, v20, v20
	v_fmac_f32_e32 v188, v21, v21
	v_fma_f32 v22, v22, v180, v168
	v_fma_f32 v23, v23, v181, v169
	v_fma_f32 v24, v24, v182, v170
	v_fma_f32 v25, v25, v183, v171
	global_store_dwordx4 v0, v[22:25], s[38:39] nt
	s_add_u32 s38, s38, 0x4000
	s_addc_u32 s39, s39, 0
	v_mul_f32_e32 v189, v22, v22
	v_fmac_f32_e32 v189, v23, v23
	v_fmac_f32_e32 v189, v24, v24
	v_fmac_f32_e32 v189, v25, v25
	v_fma_f32 v26, v26, v180, v172
	v_fma_f32 v27, v27, v181, v173
	v_fma_f32 v28, v28, v182, v174
	v_fma_f32 v29, v29, v183, v175
	global_store_dwordx4 v0, v[26:29], s[38:39] nt
	s_add_u32 s38, s38, 0x4000
	s_addc_u32 s39, s39, 0
	v_mul_f32_e32 v190, v26, v26
	v_fmac_f32_e32 v190, v27, v27
	v_fmac_f32_e32 v190, v28, v28
	v_fmac_f32_e32 v190, v29, v29
	v_fma_f32 v30, v30, v180, v176
	v_fma_f32 v31, v31, v181, v177
	v_fma_f32 v32, v32, v182, v178
	v_fma_f32 v33, v33, v183, v179
	global_store_dwordx4 v0, v[30:33], s[38:39] nt
	s_add_u32 s38, s38, 0x4000
	s_addc_u32 s39, s39, 0
	v_mul_f32_e32 v191, v30, v30
	v_fmac_f32_e32 v191, v31, v31
	v_fmac_f32_e32 v191, v32, v32
	v_fmac_f32_e32 v191, v33, v33
	v_add_f32_dpp v184, v184, v184 quad_perm:[1,0,3,2] row_mask:0xf bank_mask:0xf
	v_add_f32_dpp v185, v185, v185 quad_perm:[1,0,3,2] row_mask:0xf bank_mask:0xf
	v_add_f32_dpp v186, v186, v186 quad_perm:[1,0,3,2] row_mask:0xf bank_mask:0xf
	v_add_f32_dpp v187, v187, v187 quad_perm:[1,0,3,2] row_mask:0xf bank_mask:0xf
	v_add_f32_dpp v188, v188, v188 quad_perm:[1,0,3,2] row_mask:0xf bank_mask:0xf
	v_add_f32_dpp v189, v189, v189 quad_perm:[1,0,3,2] row_mask:0xf bank_mask:0xf
	v_add_f32_dpp v190, v190, v190 quad_perm:[1,0,3,2] row_mask:0xf bank_mask:0xf
	v_add_f32_dpp v191, v191, v191 quad_perm:[1,0,3,2] row_mask:0xf bank_mask:0xf
	v_add_f32_dpp v184, v184, v184 quad_perm:[2,3,0,1] row_mask:0xf bank_mask:0xf
	v_add_f32_dpp v185, v185, v185 quad_perm:[2,3,0,1] row_mask:0xf bank_mask:0xf
	v_add_f32_dpp v186, v186, v186 quad_perm:[2,3,0,1] row_mask:0xf bank_mask:0xf
	v_add_f32_dpp v187, v187, v187 quad_perm:[2,3,0,1] row_mask:0xf bank_mask:0xf
	v_add_f32_dpp v188, v188, v188 quad_perm:[2,3,0,1] row_mask:0xf bank_mask:0xf
	v_add_f32_dpp v189, v189, v189 quad_perm:[2,3,0,1] row_mask:0xf bank_mask:0xf
	v_add_f32_dpp v190, v190, v190 quad_perm:[2,3,0,1] row_mask:0xf bank_mask:0xf
	v_add_f32_dpp v191, v191, v191 quad_perm:[2,3,0,1] row_mask:0xf bank_mask:0xf
	v_add_f32_dpp v184, v184, v184 row_half_mirror row_mask:0xf bank_mask:0xf
	v_add_f32_dpp v185, v185, v185 row_half_mirror row_mask:0xf bank_mask:0xf
	v_add_f32_dpp v186, v186, v186 row_half_mirror row_mask:0xf bank_mask:0xf
	v_add_f32_dpp v187, v187, v187 row_half_mirror row_mask:0xf bank_mask:0xf
	v_add_f32_dpp v188, v188, v188 row_half_mirror row_mask:0xf bank_mask:0xf
	v_add_f32_dpp v189, v189, v189 row_half_mirror row_mask:0xf bank_mask:0xf
	v_add_f32_dpp v190, v190, v190 row_half_mirror row_mask:0xf bank_mask:0xf
	v_add_f32_dpp v191, v191, v191 row_half_mirror row_mask:0xf bank_mask:0xf
	v_add_f32_dpp v184, v184, v184 row_mirror row_mask:0xf bank_mask:0xf
	v_add_f32_dpp v185, v185, v185 row_mirror row_mask:0xf bank_mask:0xf
	v_add_f32_dpp v186, v186, v186 row_mirror row_mask:0xf bank_mask:0xf
	v_add_f32_dpp v187, v187, v187 row_mirror row_mask:0xf bank_mask:0xf
	v_add_f32_dpp v188, v188, v188 row_mirror row_mask:0xf bank_mask:0xf
	v_add_f32_dpp v189, v189, v189 row_mirror row_mask:0xf bank_mask:0xf
	v_add_f32_dpp v190, v190, v190 row_mirror row_mask:0xf bank_mask:0xf
	v_add_f32_dpp v191, v191, v191 row_mirror row_mask:0xf bank_mask:0xf
	v_cmp_eq_u32_e32 vcc, 0, v192
	s_and_saveexec_b64 s[0:1], vcc
	global_store_dword v194, v184, s[28:29]
	s_add_u32 s28, s28, 0x100
	s_addc_u32 s29, s29, 0
	global_store_dword v194, v185, s[28:29]
	s_add_u32 s28, s28, 0x100
	s_addc_u32 s29, s29, 0
	global_store_dword v194, v186, s[28:29]
	s_add_u32 s28, s28, 0x100
	s_addc_u32 s29, s29, 0
	global_store_dword v194, v187, s[28:29]
	s_add_u32 s28, s28, 0x100
	s_addc_u32 s29, s29, 0
	global_store_dword v194, v188, s[28:29]
	s_add_u32 s28, s28, 0x100
	s_addc_u32 s29, s29, 0
	global_store_dword v194, v189, s[28:29]
	s_add_u32 s28, s28, 0x100
	s_addc_u32 s29, s29, 0
	global_store_dword v194, v190, s[28:29]
	s_add_u32 s28, s28, 0x100
	s_addc_u32 s29, s29, 0
	global_store_dword v194, v191, s[28:29]
	s_add_u32 s28, s28, 0x100
	s_addc_u32 s29, s29, 0
	s_or_b64 exec, exec, s[0:1]
	s_add_i32 s34, s34, s30
	s_cmp_ge_i32 s34, s35
	s_cbranch_scc0 .LBB0_52

.LBB0_195:
	s_andn2_b64 vcc, exec, s[0:1]
	s_cbranch_vccnz .LBB0_301
	s_cmp_lg_u32 s2, 1
	s_mov_b64 s[0:1], -1
	s_cbranch_scc0 .LBB0_207
	s_cmp_lt_i32 s96, 1
	s_cbranch_scc1 .Lmy_norm_plain
	v_readlane_b32 s0, v243, 0
	v_and_b32_e32 v189, 63, v200
	v_lshrrev_b32_e32 v190, 4, v189
	v_and_b32_e32 v191, 15, v189
	v_lshrrev_b32_e32 v192, 6, v200
	s_and_b32 s1, s0, 7
	s_lshl_b32 s1, s1, 3
	s_lshr_b32 s2, s0, 6
	s_add_u32 s1, s1, s2
	s_lshl_b32 s1, s1, 8
	s_bfe_u32 s2, s0, 0x30003
	s_lshl_b32 s2, s2, 7
	v_lshrrev_b32_e32 v193, 1, v192
	v_and_b32_e32 v192, 1, v192
	v_lshl_add_u32 v193, v193, 7, s1
	v_lshl_add_u32 v192, v192, 6, s2
	v_lshl_add_u32 v192, v191, 2, v192
	v_add_u32_e32 v193, v193, v190
	s_lshr_b32 s3, s1, 12
	s_lshl_b32 s4, s96, 2
	s_add_u32 s3, s3, s4
	s_mul_i32 s3, s3, 0x3000
	v_readlane_b32 s4, v243, 7
	v_readlane_b32 s5, v243, 8
	s_add_u32 s4, s4, s3
	s_addc_u32 s5, s5, 0
	s_lshl_b32 s6, s96, 12
	s_add_u32 s6, s16, s6
	s_addc_u32 s7, s17, 0
	v_lshlrev_b32_e32 v194, 2, v192
	global_load_dwordx4 v[180:183], v194, s[6:7]
	s_add_u32 s38, s4, 0x1000
	s_addc_u32 s39, s5, 0
	global_load_dwordx4 v[196:199], v194, s[38:39]
	global_load_dwordx4 v[184:187], v194, s[4:5]
	v_lshl_add_u32 v194, v193, 4, v191
	v_lshlrev_b32_e32 v194, 2, v194
	v_readlane_b32 s8, v243, 5
	v_readlane_b32 s9, v243, 6
	s_nop 4
	global_load_dword v148, v194, s[8:9]
	s_add_u32 s8, s8, 0x100
	s_addc_u32 s9, s9, 0
	global_load_dword v149, v194, s[8:9]
	s_add_u32 s8, s8, 0x100
	s_addc_u32 s9, s9, 0
	global_load_dword v150, v194, s[8:9]
	s_add_u32 s8, s8, 0x100
	s_addc_u32 s9, s9, 0
	global_load_dword v151, v194, s[8:9]
	s_add_u32 s8, s8, 0x100
	s_addc_u32 s9, s9, 0
	global_load_dword v152, v194, s[8:9]
	s_add_u32 s8, s8, 0x100
	s_addc_u32 s9, s9, 0
	global_load_dword v153, v194, s[8:9]
	s_add_u32 s8, s8, 0x100
	s_addc_u32 s9, s9, 0
	global_load_dword v154, v194, s[8:9]
	s_add_u32 s8, s8, 0x100
	s_addc_u32 s9, s9, 0
	global_load_dword v155, v194, s[8:9]
	s_add_u32 s8, s8, 0x100
	s_addc_u32 s9, s9, 0
	global_load_dword v156, v194, s[8:9]
	s_add_u32 s8, s8, 0x100
	s_addc_u32 s9, s9, 0
	global_load_dword v157, v194, s[8:9]
	s_add_u32 s8, s8, 0x100
	s_addc_u32 s9, s9, 0
	global_load_dword v158, v194, s[8:9]
	s_add_u32 s8, s8, 0x100
	s_addc_u32 s9, s9, 0
	global_load_dword v159, v194, s[8:9]
	s_add_u32 s8, s8, 0x100
	s_addc_u32 s9, s9, 0
	global_load_dword v160, v194, s[8:9]
	s_add_u32 s8, s8, 0x100
	s_addc_u32 s9, s9, 0
	global_load_dword v161, v194, s[8:9]
	s_add_u32 s8, s8, 0x100
	s_addc_u32 s9, s9, 0
	global_load_dword v162, v194, s[8:9]
	s_add_u32 s8, s8, 0x100
	s_addc_u32 s9, s9, 0
	global_load_dword v163, v194, s[8:9]
	s_add_u32 s8, s8, 0x100
	s_addc_u32 s9, s9, 0
	global_load_dword v164, v194, s[8:9]
	s_add_u32 s8, s8, 0x100
	s_addc_u32 s9, s9, 0
	global_load_dword v165, v194, s[8:9]
	s_add_u32 s8, s8, 0x100
	s_addc_u32 s9, s9, 0
	global_load_dword v166, v194, s[8:9]
	s_add_u32 s8, s8, 0x100
	s_addc_u32 s9, s9, 0
	global_load_dword v167, v194, s[8:9]
	s_add_u32 s8, s8, 0x100
	s_addc_u32 s9, s9, 0
	global_load_dword v168, v194, s[8:9]
	s_add_u32 s8, s8, 0x100
	s_addc_u32 s9, s9, 0
	global_load_dword v169, v194, s[8:9]
	s_add_u32 s8, s8, 0x100
	s_addc_u32 s9, s9, 0
	global_load_dword v170, v194, s[8:9]
	s_add_u32 s8, s8, 0x100
	s_addc_u32 s9, s9, 0
	global_load_dword v171, v194, s[8:9]
	s_add_u32 s8, s8, 0x100
	s_addc_u32 s9, s9, 0
	global_load_dword v172, v194, s[8:9]
	s_add_u32 s8, s8, 0x100
	s_addc_u32 s9, s9, 0
	global_load_dword v173, v194, s[8:9]
	s_add_u32 s8, s8, 0x100
	s_addc_u32 s9, s9, 0
	global_load_dword v174, v194, s[8:9]
	s_add_u32 s8, s8, 0x100
	s_addc_u32 s9, s9, 0
	global_load_dword v175, v194, s[8:9]
	s_add_u32 s8, s8, 0x100
	s_addc_u32 s9, s9, 0
	global_load_dword v176, v194, s[8:9]
	s_add_u32 s8, s8, 0x100
	s_addc_u32 s9, s9, 0
	global_load_dword v177, v194, s[8:9]
	s_add_u32 s8, s8, 0x100
	s_addc_u32 s9, s9, 0
	global_load_dword v178, v194, s[8:9]
	s_add_u32 s8, s8, 0x100
	s_addc_u32 s9, s9, 0
	global_load_dword v179, v194, s[8:9]
	s_add_u32 s8, s8, 0x100
	s_addc_u32 s9, s9, 0
	v_lshrrev_b32_e32 v188, 1, v193
	v_lshlrev_b32_e32 v188, 5, v188
	v_lshrrev_b32_e32 v190, 5, v192
	v_add_u32_e32 v188, v188, v190
	v_lshlrev_b32_e32 v188, 6, v188
	v_and_b32_e32 v190, 1, v193
	v_lshl_add_u32 v188, v190, 5, v188
	v_and_b32_e32 v190, 31, v192
	v_add_u32_e32 v188, v188, v190
	v_lshlrev_b32_e32 v188, 1, v188
	s_mov_b64 s[36:37], s[62:63]
	s_waitcnt vmcnt(32)
	v_add_f32_e32 v196, 1.0, v196
	v_add_f32_e32 v197, 1.0, v197
	v_add_f32_e32 v198, 1.0, v198
	v_add_f32_e32 v199, 1.0, v199
	v_mul_f32_e32 v180, v180, v196
	v_mul_f32_e32 v181, v181, v197
	v_mul_f32_e32 v182, v182, v198
	v_mul_f32_e32 v183, v183, v199
	s_waitcnt vmcnt(0)
	v_add_f32_dpp v148, v148, v148 quad_perm:[1,0,3,2] row_mask:0xf bank_mask:0xf
	v_add_f32_dpp v149, v149, v149 quad_perm:[1,0,3,2] row_mask:0xf bank_mask:0xf
	v_add_f32_dpp v150, v150, v150 quad_perm:[1,0,3,2] row_mask:0xf bank_mask:0xf
	v_add_f32_dpp v151, v151, v151 quad_perm:[1,0,3,2] row_mask:0xf bank_mask:0xf
	v_add_f32_dpp v152, v152, v152 quad_perm:[1,0,3,2] row_mask:0xf bank_mask:0xf
	v_add_f32_dpp v153, v153, v153 quad_perm:[1,0,3,2] row_mask:0xf bank_mask:0xf
	v_add_f32_dpp v154, v154, v154 quad_perm:[1,0,3,2] row_mask:0xf bank_mask:0xf
	v_add_f32_dpp v155, v155, v155 quad_perm:[1,0,3,2] row_mask:0xf bank_mask:0xf
	v_add_f32_dpp v156, v156, v156 quad_perm:[1,0,3,2] row_mask:0xf bank_mask:0xf
	v_add_f32_dpp v157, v157, v157 quad_perm:[1,0,3,2] row_mask:0xf bank_mask:0xf
	v_add_f32_dpp v158, v158, v158 quad_perm:[1,0,3,2] row_mask:0xf bank_mask:0xf
	v_add_f32_dpp v159, v159, v159 quad_perm:[1,0,3,2] row_mask:0xf bank_mask:0xf
	v_add_f32_dpp v160, v160, v160 quad_perm:[1,0,3,2] row_mask:0xf bank_mask:0xf
	v_add_f32_dpp v161, v161, v161 quad_perm:[1,0,3,2] row_mask:0xf bank_mask:0xf
	v_add_f32_dpp v162, v162, v162 quad_perm:[1,0,3,2] row_mask:0xf bank_mask:0xf
	v_add_f32_dpp v163, v163, v163 quad_perm:[1,0,3,2] row_mask:0xf bank_mask:0xf
	v_add_f32_dpp v164, v164, v164 quad_perm:[1,0,3,2] row_mask:0xf bank_mask:0xf
	v_add_f32_dpp v165, v165, v165 quad_perm:[1,0,3,2] row_mask:0xf bank_mask:0xf
	v_add_f32_dpp v166, v166, v166 quad_perm:[1,0,3,2] row_mask:0xf bank_mask:0xf
	v_add_f32_dpp v167, v167, v167 quad_perm:[1,0,3,2] row_mask:0xf bank_mask:0xf
	v_add_f32_dpp v168, v168, v168 quad_perm:[1,0,3,2] row_mask:0xf bank_mask:0xf
	v_add_f32_dpp v169, v169, v169 quad_perm:[1,0,3,2] row_mask:0xf bank_mask:0xf
	v_add_f32_dpp v170, v170, v170 quad_perm:[1,0,3,2] row_mask:0xf bank_mask:0xf
	v_add_f32_dpp v171, v171, v171 quad_perm:[1,0,3,2] row_mask:0xf bank_mask:0xf
	v_add_f32_dpp v172, v172, v172 quad_perm:[1,0,3,2] row_mask:0xf bank_mask:0xf
	v_add_f32_dpp v173, v173, v173 quad_perm:[1,0,3,2] row_mask:0xf bank_mask:0xf
	v_add_f32_dpp v174, v174, v174 quad_perm:[1,0,3,2] row_mask:0xf bank_mask:0xf
	v_add_f32_dpp v175, v175, v175 quad_perm:[1,0,3,2] row_mask:0xf bank_mask:0xf
	v_add_f32_dpp v176, v176, v176 quad_perm:[1,0,3,2] row_mask:0xf bank_mask:0xf
	v_add_f32_dpp v177, v177, v177 quad_perm:[1,0,3,2] row_mask:0xf bank_mask:0xf
	v_add_f32_dpp v178, v178, v178 quad_perm:[1,0,3,2] row_mask:0xf bank_mask:0xf
	v_add_f32_dpp v179, v179, v179 quad_perm:[1,0,3,2] row_mask:0xf bank_mask:0xf
	v_add_f32_dpp v148, v148, v148 quad_perm:[2,3,0,1] row_mask:0xf bank_mask:0xf
	v_add_f32_dpp v149, v149, v149 quad_perm:[2,3,0,1] row_mask:0xf bank_mask:0xf
	v_add_f32_dpp v150, v150, v150 quad_perm:[2,3,0,1] row_mask:0xf bank_mask:0xf
	v_add_f32_dpp v151, v151, v151 quad_perm:[2,3,0,1] row_mask:0xf bank_mask:0xf
	v_add_f32_dpp v152, v152, v152 quad_perm:[2,3,0,1] row_mask:0xf bank_mask:0xf
	v_add_f32_dpp v153, v153, v153 quad_perm:[2,3,0,1] row_mask:0xf bank_mask:0xf
	v_add_f32_dpp v154, v154, v154 quad_perm:[2,3,0,1] row_mask:0xf bank_mask:0xf
	v_add_f32_dpp v155, v155, v155 quad_perm:[2,3,0,1] row_mask:0xf bank_mask:0xf
	v_add_f32_dpp v156, v156, v156 quad_perm:[2,3,0,1] row_mask:0xf bank_mask:0xf
	v_add_f32_dpp v157, v157, v157 quad_perm:[2,3,0,1] row_mask:0xf bank_mask:0xf
	v_add_f32_dpp v158, v158, v158 quad_perm:[2,3,0,1] row_mask:0xf bank_mask:0xf
	v_add_f32_dpp v159, v159, v159 quad_perm:[2,3,0,1] row_mask:0xf bank_mask:0xf
	v_add_f32_dpp v160, v160, v160 quad_perm:[2,3,0,1] row_mask:0xf bank_mask:0xf
	v_add_f32_dpp v161, v161, v161 quad_perm:[2,3,0,1] row_mask:0xf bank_mask:0xf
	v_add_f32_dpp v162, v162, v162 quad_perm:[2,3,0,1] row_mask:0xf bank_mask:0xf
	v_add_f32_dpp v163, v163, v163 quad_perm:[2,3,0,1] row_mask:0xf bank_mask:0xf
	v_add_f32_dpp v164, v164, v164 quad_perm:[2,3,0,1] row_mask:0xf bank_mask:0xf
	v_add_f32_dpp v165, v165, v165 quad_perm:[2,3,0,1] row_mask:0xf bank_mask:0xf
	v_add_f32_dpp v166, v166, v166 quad_perm:[2,3,0,1] row_mask:0xf bank_mask:0xf
	v_add_f32_dpp v167, v167, v167 quad_perm:[2,3,0,1] row_mask:0xf bank_mask:0xf
	v_add_f32_dpp v168, v168, v168 quad_perm:[2,3,0,1] row_mask:0xf bank_mask:0xf
	v_add_f32_dpp v169, v169, v169 quad_perm:[2,3,0,1] row_mask:0xf bank_mask:0xf
	v_add_f32_dpp v170, v170, v170 quad_perm:[2,3,0,1] row_mask:0xf bank_mask:0xf
	v_add_f32_dpp v171, v171, v171 quad_perm:[2,3,0,1] row_mask:0xf bank_mask:0xf
	v_add_f32_dpp v172, v172, v172 quad_perm:[2,3,0,1] row_mask:0xf bank_mask:0xf
	v_add_f32_dpp v173, v173, v173 quad_perm:[2,3,0,1] row_mask:0xf bank_mask:0xf
	v_add_f32_dpp v174, v174, v174 quad_perm:[2,3,0,1] row_mask:0xf bank_mask:0xf
	v_add_f32_dpp v175, v175, v175 quad_perm:[2,3,0,1] row_mask:0xf bank_mask:0xf
	v_add_f32_dpp v176, v176, v176 quad_perm:[2,3,0,1] row_mask:0xf bank_mask:0xf
	v_add_f32_dpp v177, v177, v177 quad_perm:[2,3,0,1] row_mask:0xf bank_mask:0xf
	v_add_f32_dpp v178, v178, v178 quad_perm:[2,3,0,1] row_mask:0xf bank_mask:0xf
	v_add_f32_dpp v179, v179, v179 quad_perm:[2,3,0,1] row_mask:0xf bank_mask:0xf
	v_add_f32_dpp v148, v148, v148 row_half_mirror row_mask:0xf bank_mask:0xf
	v_add_f32_dpp v149, v149, v149 row_half_mirror row_mask:0xf bank_mask:0xf
	v_add_f32_dpp v150, v150, v150 row_half_mirror row_mask:0xf bank_mask:0xf
	v_add_f32_dpp v151, v151, v151 row_half_mirror row_mask:0xf bank_mask:0xf
	v_add_f32_dpp v152, v152, v152 row_half_mirror row_mask:0xf bank_mask:0xf
	v_add_f32_dpp v153, v153, v153 row_half_mirror row_mask:0xf bank_mask:0xf
	v_add_f32_dpp v154, v154, v154 row_half_mirror row_mask:0xf bank_mask:0xf
	v_add_f32_dpp v155, v155, v155 row_half_mirror row_mask:0xf bank_mask:0xf
	v_add_f32_dpp v156, v156, v156 row_half_mirror row_mask:0xf bank_mask:0xf
	v_add_f32_dpp v157, v157, v157 row_half_mirror row_mask:0xf bank_mask:0xf
	v_add_f32_dpp v158, v158, v158 row_half_mirror row_mask:0xf bank_mask:0xf
	v_add_f32_dpp v159, v159, v159 row_half_mirror row_mask:0xf bank_mask:0xf
	v_add_f32_dpp v160, v160, v160 row_half_mirror row_mask:0xf bank_mask:0xf
	v_add_f32_dpp v161, v161, v161 row_half_mirror row_mask:0xf bank_mask:0xf
	v_add_f32_dpp v162, v162, v162 row_half_mirror row_mask:0xf bank_mask:0xf
	v_add_f32_dpp v163, v163, v163 row_half_mirror row_mask:0xf bank_mask:0xf
	v_add_f32_dpp v164, v164, v164 row_half_mirror row_mask:0xf bank_mask:0xf
	v_add_f32_dpp v165, v165, v165 row_half_mirror row_mask:0xf bank_mask:0xf
	v_add_f32_dpp v166, v166, v166 row_half_mirror row_mask:0xf bank_mask:0xf
	v_add_f32_dpp v167, v167, v167 row_half_mirror row_mask:0xf bank_mask:0xf
	v_add_f32_dpp v168, v168, v168 row_half_mirror row_mask:0xf bank_mask:0xf
	v_add_f32_dpp v169, v169, v169 row_half_mirror row_mask:0xf bank_mask:0xf
	v_add_f32_dpp v170, v170, v170 row_half_mirror row_mask:0xf bank_mask:0xf
	v_add_f32_dpp v171, v171, v171 row_half_mirror row_mask:0xf bank_mask:0xf
	v_add_f32_dpp v172, v172, v172 row_half_mirror row_mask:0xf bank_mask:0xf
	v_add_f32_dpp v173, v173, v173 row_half_mirror row_mask:0xf bank_mask:0xf
	v_add_f32_dpp v174, v174, v174 row_half_mirror row_mask:0xf bank_mask:0xf
	v_add_f32_dpp v175, v175, v175 row_half_mirror row_mask:0xf bank_mask:0xf
	v_add_f32_dpp v176, v176, v176 row_half_mirror row_mask:0xf bank_mask:0xf
	v_add_f32_dpp v177, v177, v177 row_half_mirror row_mask:0xf bank_mask:0xf
	v_add_f32_dpp v178, v178, v178 row_half_mirror row_mask:0xf bank_mask:0xf
	v_add_f32_dpp v179, v179, v179 row_half_mirror row_mask:0xf bank_mask:0xf
	v_add_f32_dpp v148, v148, v148 row_mirror row_mask:0xf bank_mask:0xf
	v_add_f32_dpp v149, v149, v149 row_mirror row_mask:0xf bank_mask:0xf
	v_add_f32_dpp v150, v150, v150 row_mirror row_mask:0xf bank_mask:0xf
	v_add_f32_dpp v151, v151, v151 row_mirror row_mask:0xf bank_mask:0xf
	v_add_f32_dpp v152, v152, v152 row_mirror row_mask:0xf bank_mask:0xf
	v_add_f32_dpp v153, v153, v153 row_mirror row_mask:0xf bank_mask:0xf
	v_add_f32_dpp v154, v154, v154 row_mirror row_mask:0xf bank_mask:0xf
	v_add_f32_dpp v155, v155, v155 row_mirror row_mask:0xf bank_mask:0xf
	v_add_f32_dpp v156, v156, v156 row_mirror row_mask:0xf bank_mask:0xf
	v_add_f32_dpp v157, v157, v157 row_mirror row_mask:0xf bank_mask:0xf
	v_add_f32_dpp v158, v158, v158 row_mirror row_mask:0xf bank_mask:0xf
	v_add_f32_dpp v159, v159, v159 row_mirror row_mask:0xf bank_mask:0xf
	v_add_f32_dpp v160, v160, v160 row_mirror row_mask:0xf bank_mask:0xf
	v_add_f32_dpp v161, v161, v161 row_mirror row_mask:0xf bank_mask:0xf
	v_add_f32_dpp v162, v162, v162 row_mirror row_mask:0xf bank_mask:0xf
	v_add_f32_dpp v163, v163, v163 row_mirror row_mask:0xf bank_mask:0xf
	v_add_f32_dpp v164, v164, v164 row_mirror row_mask:0xf bank_mask:0xf
	v_add_f32_dpp v165, v165, v165 row_mirror row_mask:0xf bank_mask:0xf
	v_add_f32_dpp v166, v166, v166 row_mirror row_mask:0xf bank_mask:0xf
	v_add_f32_dpp v167, v167, v167 row_mirror row_mask:0xf bank_mask:0xf
	v_add_f32_dpp v168, v168, v168 row_mirror row_mask:0xf bank_mask:0xf
	v_add_f32_dpp v169, v169, v169 row_mirror row_mask:0xf bank_mask:0xf
	v_add_f32_dpp v170, v170, v170 row_mirror row_mask:0xf bank_mask:0xf
	v_add_f32_dpp v171, v171, v171 row_mirror row_mask:0xf bank_mask:0xf
	v_add_f32_dpp v172, v172, v172 row_mirror row_mask:0xf bank_mask:0xf
	v_add_f32_dpp v173, v173, v173 row_mirror row_mask:0xf bank_mask:0xf
	v_add_f32_dpp v174, v174, v174 row_mirror row_mask:0xf bank_mask:0xf
	v_add_f32_dpp v175, v175, v175 row_mirror row_mask:0xf bank_mask:0xf
	v_add_f32_dpp v176, v176, v176 row_mirror row_mask:0xf bank_mask:0xf
	v_add_f32_dpp v177, v177, v177 row_mirror row_mask:0xf bank_mask:0xf
	v_add_f32_dpp v178, v178, v178 row_mirror row_mask:0xf bank_mask:0xf
	v_add_f32_dpp v179, v179, v179 row_mirror row_mask:0xf bank_mask:0xf
	v_fmamk_f32 v148, v148, 0x3a800000, v202
	v_cmp_gt_f32_e32 vcc, s74, v148
	v_mul_f32_e32 v190, 0x4b800000, v148
	s_nop 0
	v_cndmask_b32_e32 v148, v148, v190, vcc
	v_rsq_f32_e32 v148, v148
	s_nop 0
	v_mul_f32_e32 v190, 0x45800000, v148
	v_cndmask_b32_e32 v148, v148, v190, vcc
	v_mul_f32_e32 v98, v98, v148
	v_mul_f32_e32 v99, v99, v148
	v_mul_f32_e32 v100, v100, v148
	v_mul_f32_e32 v101, v101, v148
	v_fma_f32 v98, v180, v98, v184
	v_fma_f32 v99, v181, v99, v185
	v_fma_f32 v100, v182, v100, v186
	v_fma_f32 v101, v183, v101, v187
	v_cvt_pk_bf16_f32 v190, v98, v99
	v_cvt_pk_bf16_f32 v191, v100, v101
	global_store_dwordx2 v188, v[190:191], s[36:37]
	s_add_u32 s36, s36, 0x2000
	s_addc_u32 s37, s37, 0
	v_fmamk_f32 v149, v149, 0x3a800000, v202
	v_cmp_gt_f32_e32 vcc, s74, v149
	v_mul_f32_e32 v190, 0x4b800000, v149
	s_nop 0
	v_cndmask_b32_e32 v149, v149, v190, vcc
	v_rsq_f32_e32 v149, v149
	s_nop 0
	v_mul_f32_e32 v190, 0x45800000, v149
	v_cndmask_b32_e32 v149, v149, v190, vcc
	v_mul_f32_e32 v102, v102, v149
	v_mul_f32_e32 v103, v103, v149
	v_mul_f32_e32 v104, v104, v149
	v_mul_f32_e32 v105, v105, v149
	v_fma_f32 v102, v180, v102, v184
	v_fma_f32 v103, v181, v103, v185
	v_fma_f32 v104, v182, v104, v186
	v_fma_f32 v105, v183, v105, v187
	v_cvt_pk_bf16_f32 v190, v102, v103
	v_cvt_pk_bf16_f32 v191, v104, v105
	global_store_dwordx2 v188, v[190:191], s[36:37]
	s_add_u32 s36, s36, 0x2000
	s_addc_u32 s37, s37, 0
	v_fmamk_f32 v150, v150, 0x3a800000, v202
	v_cmp_gt_f32_e32 vcc, s74, v150
	v_mul_f32_e32 v190, 0x4b800000, v150
	s_nop 0
	v_cndmask_b32_e32 v150, v150, v190, vcc
	v_rsq_f32_e32 v150, v150
	s_nop 0
	v_mul_f32_e32 v190, 0x45800000, v150
	v_cndmask_b32_e32 v150, v150, v190, vcc
	v_mul_f32_e32 v106, v106, v150
	v_mul_f32_e32 v107, v107, v150
	v_mul_f32_e32 v108, v108, v150
	v_mul_f32_e32 v109, v109, v150
	v_fma_f32 v106, v180, v106, v184
	v_fma_f32 v107, v181, v107, v185
	v_fma_f32 v108, v182, v108, v186
	v_fma_f32 v109, v183, v109, v187
	v_cvt_pk_bf16_f32 v190, v106, v107
	v_cvt_pk_bf16_f32 v191, v108, v109
	global_store_dwordx2 v188, v[190:191], s[36:37]
	s_add_u32 s36, s36, 0x2000
	s_addc_u32 s37, s37, 0
	v_fmamk_f32 v151, v151, 0x3a800000, v202
	v_cmp_gt_f32_e32 vcc, s74, v151
	v_mul_f32_e32 v190, 0x4b800000, v151
	s_nop 0
	v_cndmask_b32_e32 v151, v151, v190, vcc
	v_rsq_f32_e32 v151, v151
	s_nop 0
	v_mul_f32_e32 v190, 0x45800000, v151
	v_cndmask_b32_e32 v151, v151, v190, vcc
	v_mul_f32_e32 v110, v110, v151
	v_mul_f32_e32 v111, v111, v151
	v_mul_f32_e32 v112, v112, v151
	v_mul_f32_e32 v113, v113, v151
	v_fma_f32 v110, v180, v110, v184
	v_fma_f32 v111, v181, v111, v185
	v_fma_f32 v112, v182, v112, v186
	v_fma_f32 v113, v183, v113, v187
	v_cvt_pk_bf16_f32 v190, v110, v111
	v_cvt_pk_bf16_f32 v191, v112, v113
	global_store_dwordx2 v188, v[190:191], s[36:37]
	s_add_u32 s36, s36, 0x2000
	s_addc_u32 s37, s37, 0
	v_fmamk_f32 v152, v152, 0x3a800000, v202
	v_cmp_gt_f32_e32 vcc, s74, v152
	v_mul_f32_e32 v190, 0x4b800000, v152
	s_nop 0
	v_cndmask_b32_e32 v152, v152, v190, vcc
	v_rsq_f32_e32 v152, v152
	s_nop 0
	v_mul_f32_e32 v190, 0x45800000, v152
	v_cndmask_b32_e32 v152, v152, v190, vcc
	v_mul_f32_e32 v114, v114, v152
	v_mul_f32_e32 v115, v115, v152
	v_mul_f32_e32 v116, v116, v152
	v_mul_f32_e32 v117, v117, v152
	v_fma_f32 v114, v180, v114, v184
	v_fma_f32 v115, v181, v115, v185
	v_fma_f32 v116, v182, v116, v186
	v_fma_f32 v117, v183, v117, v187
	v_cvt_pk_bf16_f32 v190, v114, v115
	v_cvt_pk_bf16_f32 v191, v116, v117
	global_store_dwordx2 v188, v[190:191], s[36:37]
	s_add_u32 s36, s36, 0x2000
	s_addc_u32 s37, s37, 0
	v_fmamk_f32 v153, v153, 0x3a800000, v202
	v_cmp_gt_f32_e32 vcc, s74, v153
	v_mul_f32_e32 v190, 0x4b800000, v153
	s_nop 0
	v_cndmask_b32_e32 v153, v153, v190, vcc
	v_rsq_f32_e32 v153, v153
	s_nop 0
	v_mul_f32_e32 v190, 0x45800000, v153
	v_cndmask_b32_e32 v153, v153, v190, vcc
	v_mul_f32_e32 v118, v118, v153
	v_mul_f32_e32 v119, v119, v153
	v_mul_f32_e32 v120, v120, v153
	v_mul_f32_e32 v121, v121, v153
	v_fma_f32 v118, v180, v118, v184
	v_fma_f32 v119, v181, v119, v185
	v_fma_f32 v120, v182, v120, v186
	v_fma_f32 v121, v183, v121, v187
	v_cvt_pk_bf16_f32 v190, v118, v119
	v_cvt_pk_bf16_f32 v191, v120, v121
	global_store_dwordx2 v188, v[190:191], s[36:37]
	s_add_u32 s36, s36, 0x2000
	s_addc_u32 s37, s37, 0
	v_fmamk_f32 v154, v154, 0x3a800000, v202
	v_cmp_gt_f32_e32 vcc, s74, v154
	v_mul_f32_e32 v190, 0x4b800000, v154
	s_nop 0
	v_cndmask_b32_e32 v154, v154, v190, vcc
	v_rsq_f32_e32 v154, v154
	s_nop 0
	v_mul_f32_e32 v190, 0x45800000, v154
	v_cndmask_b32_e32 v154, v154, v190, vcc
	v_mul_f32_e32 v122, v122, v154
	v_mul_f32_e32 v123, v123, v154
	v_mul_f32_e32 v124, v124, v154
	v_mul_f32_e32 v125, v125, v154
	v_fma_f32 v122, v180, v122, v184
	v_fma_f32 v123, v181, v123, v185
	v_fma_f32 v124, v182, v124, v186
	v_fma_f32 v125, v183, v125, v187
	v_cvt_pk_bf16_f32 v190, v122, v123
	v_cvt_pk_bf16_f32 v191, v124, v125
	global_store_dwordx2 v188, v[190:191], s[36:37]
	s_add_u32 s36, s36, 0x2000
	s_addc_u32 s37, s37, 0
	v_fmamk_f32 v155, v155, 0x3a800000, v202
	v_cmp_gt_f32_e32 vcc, s74, v155
	v_mul_f32_e32 v190, 0x4b800000, v155
	s_nop 0
	v_cndmask_b32_e32 v155, v155, v190, vcc
	v_rsq_f32_e32 v155, v155
	s_nop 0
	v_mul_f32_e32 v190, 0x45800000, v155
	v_cndmask_b32_e32 v155, v155, v190, vcc
	v_mul_f32_e32 v126, v126, v155
	v_mul_f32_e32 v127, v127, v155
	v_mul_f32_e32 v128, v128, v155
	v_mul_f32_e32 v129, v129, v155
	v_fma_f32 v126, v180, v126, v184
	v_fma_f32 v127, v181, v127, v185
	v_fma_f32 v128, v182, v128, v186
	v_fma_f32 v129, v183, v129, v187
	v_cvt_pk_bf16_f32 v190, v126, v127
	v_cvt_pk_bf16_f32 v191, v128, v129
	global_store_dwordx2 v188, v[190:191], s[36:37]
	s_add_u32 s36, s36, 0x2000
	s_addc_u32 s37, s37, 0
	v_fmamk_f32 v156, v156, 0x3a800000, v202
	v_cmp_gt_f32_e32 vcc, s74, v156
	v_mul_f32_e32 v190, 0x4b800000, v156
	s_nop 0
	v_cndmask_b32_e32 v156, v156, v190, vcc
	v_rsq_f32_e32 v156, v156
	s_nop 0
	v_mul_f32_e32 v190, 0x45800000, v156
	v_cndmask_b32_e32 v156, v156, v190, vcc
	v_mul_f32_e32 v66, v66, v156
	v_mul_f32_e32 v67, v67, v156
	v_mul_f32_e32 v68, v68, v156
	v_mul_f32_e32 v69, v69, v156
	v_fma_f32 v66, v180, v66, v184
	v_fma_f32 v67, v181, v67, v185
	v_fma_f32 v68, v182, v68, v186
	v_fma_f32 v69, v183, v69, v187
	v_cvt_pk_bf16_f32 v190, v66, v67
	v_cvt_pk_bf16_f32 v191, v68, v69
	global_store_dwordx2 v188, v[190:191], s[36:37]
	s_add_u32 s36, s36, 0x2000
	s_addc_u32 s37, s37, 0
	v_fmamk_f32 v157, v157, 0x3a800000, v202
	v_cmp_gt_f32_e32 vcc, s74, v157
	v_mul_f32_e32 v190, 0x4b800000, v157
	s_nop 0
	v_cndmask_b32_e32 v157, v157, v190, vcc
	v_rsq_f32_e32 v157, v157
	s_nop 0
	v_mul_f32_e32 v190, 0x45800000, v157
	v_cndmask_b32_e32 v157, v157, v190, vcc
	v_mul_f32_e32 v70, v70, v157
	v_mul_f32_e32 v71, v71, v157
	v_mul_f32_e32 v72, v72, v157
	v_mul_f32_e32 v73, v73, v157
	v_fma_f32 v70, v180, v70, v184
	v_fma_f32 v71, v181, v71, v185
	v_fma_f32 v72, v182, v72, v186
	v_fma_f32 v73, v183, v73, v187
	v_cvt_pk_bf16_f32 v190, v70, v71
	v_cvt_pk_bf16_f32 v191, v72, v73
	global_store_dwordx2 v188, v[190:191], s[36:37]
	s_add_u32 s36, s36, 0x2000
	s_addc_u32 s37, s37, 0
	v_fmamk_f32 v158, v158, 0x3a800000, v202
	v_cmp_gt_f32_e32 vcc, s74, v158
	v_mul_f32_e32 v190, 0x4b800000, v158
	s_nop 0
	v_cndmask_b32_e32 v158, v158, v190, vcc
	v_rsq_f32_e32 v158, v158
	s_nop 0
	v_mul_f32_e32 v190, 0x45800000, v158
	v_cndmask_b32_e32 v158, v158, v190, vcc
	v_mul_f32_e32 v74, v74, v158
	v_mul_f32_e32 v75, v75, v158
	v_mul_f32_e32 v76, v76, v158
	v_mul_f32_e32 v77, v77, v158
	v_fma_f32 v74, v180, v74, v184
	v_fma_f32 v75, v181, v75, v185
	v_fma_f32 v76, v182, v76, v186
	v_fma_f32 v77, v183, v77, v187
	v_cvt_pk_bf16_f32 v190, v74, v75
	v_cvt_pk_bf16_f32 v191, v76, v77
	global_store_dwordx2 v188, v[190:191], s[36:37]
	s_add_u32 s36, s36, 0x2000
	s_addc_u32 s37, s37, 0
	v_fmamk_f32 v159, v159, 0x3a800000, v202
	v_cmp_gt_f32_e32 vcc, s74, v159
	v_mul_f32_e32 v190, 0x4b800000, v159
	s_nop 0
	v_cndmask_b32_e32 v159, v159, v190, vcc
	v_rsq_f32_e32 v159, v159
	s_nop 0
	v_mul_f32_e32 v190, 0x45800000, v159
	v_cndmask_b32_e32 v159, v159, v190, vcc
	v_mul_f32_e32 v78, v78, v159
	v_mul_f32_e32 v79, v79, v159
	v_mul_f32_e32 v80, v80, v159
	v_mul_f32_e32 v81, v81, v159
	v_fma_f32 v78, v180, v78, v184
	v_fma_f32 v79, v181, v79, v185
	v_fma_f32 v80, v182, v80, v186
	v_fma_f32 v81, v183, v81, v187
	v_cvt_pk_bf16_f32 v190, v78, v79
	v_cvt_pk_bf16_f32 v191, v80, v81
	global_store_dwordx2 v188, v[190:191], s[36:37]
	s_add_u32 s36, s36, 0x2000
	s_addc_u32 s37, s37, 0
	v_fmamk_f32 v160, v160, 0x3a800000, v202
	v_cmp_gt_f32_e32 vcc, s74, v160
	v_mul_f32_e32 v190, 0x4b800000, v160
	s_nop 0
	v_cndmask_b32_e32 v160, v160, v190, vcc
	v_rsq_f32_e32 v160, v160
	s_nop 0
	v_mul_f32_e32 v190, 0x45800000, v160
	v_cndmask_b32_e32 v160, v160, v190, vcc
	v_mul_f32_e32 v82, v82, v160
	v_mul_f32_e32 v83, v83, v160
	v_mul_f32_e32 v84, v84, v160
	v_mul_f32_e32 v85, v85, v160
	v_fma_f32 v82, v180, v82, v184
	v_fma_f32 v83, v181, v83, v185
	v_fma_f32 v84, v182, v84, v186
	v_fma_f32 v85, v183, v85, v187
	v_cvt_pk_bf16_f32 v190, v82, v83
	v_cvt_pk_bf16_f32 v191, v84, v85
	global_store_dwordx2 v188, v[190:191], s[36:37]
	s_add_u32 s36, s36, 0x2000
	s_addc_u32 s37, s37, 0
	v_fmamk_f32 v161, v161, 0x3a800000, v202
	v_cmp_gt_f32_e32 vcc, s74, v161
	v_mul_f32_e32 v190, 0x4b800000, v161
	s_nop 0
	v_cndmask_b32_e32 v161, v161, v190, vcc
	v_rsq_f32_e32 v161, v161
	s_nop 0
	v_mul_f32_e32 v190, 0x45800000, v161
	v_cndmask_b32_e32 v161, v161, v190, vcc
	v_mul_f32_e32 v86, v86, v161
	v_mul_f32_e32 v87, v87, v161
	v_mul_f32_e32 v88, v88, v161
	v_mul_f32_e32 v89, v89, v161
	v_fma_f32 v86, v180, v86, v184
	v_fma_f32 v87, v181, v87, v185
	v_fma_f32 v88, v182, v88, v186
	v_fma_f32 v89, v183, v89, v187
	v_cvt_pk_bf16_f32 v190, v86, v87
	v_cvt_pk_bf16_f32 v191, v88, v89
	global_store_dwordx2 v188, v[190:191], s[36:37]
	s_add_u32 s36, s36, 0x2000
	s_addc_u32 s37, s37, 0
	v_fmamk_f32 v162, v162, 0x3a800000, v202
	v_cmp_gt_f32_e32 vcc, s74, v162
	v_mul_f32_e32 v190, 0x4b800000, v162
	s_nop 0
	v_cndmask_b32_e32 v162, v162, v190, vcc
	v_rsq_f32_e32 v162, v162
	s_nop 0
	v_mul_f32_e32 v190, 0x45800000, v162
	v_cndmask_b32_e32 v162, v162, v190, vcc
	v_mul_f32_e32 v90, v90, v162
	v_mul_f32_e32 v91, v91, v162
	v_mul_f32_e32 v92, v92, v162
	v_mul_f32_e32 v93, v93, v162
	v_fma_f32 v90, v180, v90, v184
	v_fma_f32 v91, v181, v91, v185
	v_fma_f32 v92, v182, v92, v186
	v_fma_f32 v93, v183, v93, v187
	v_cvt_pk_bf16_f32 v190, v90, v91
	v_cvt_pk_bf16_f32 v191, v92, v93
	global_store_dwordx2 v188, v[190:191], s[36:37]
	s_add_u32 s36, s36, 0x2000
	s_addc_u32 s37, s37, 0
	v_fmamk_f32 v163, v163, 0x3a800000, v202
	v_cmp_gt_f32_e32 vcc, s74, v163
	v_mul_f32_e32 v190, 0x4b800000, v163
	s_nop 0
	v_cndmask_b32_e32 v163, v163, v190, vcc
	v_rsq_f32_e32 v163, v163
	s_nop 0
	v_mul_f32_e32 v190, 0x45800000, v163
	v_cndmask_b32_e32 v163, v163, v190, vcc
	v_mul_f32_e32 v94, v94, v163
	v_mul_f32_e32 v95, v95, v163
	v_mul_f32_e32 v96, v96, v163
	v_mul_f32_e32 v97, v97, v163
	v_fma_f32 v94, v180, v94, v184
	v_fma_f32 v95, v181, v95, v185
	v_fma_f32 v96, v182, v96, v186
	v_fma_f32 v97, v183, v97, v187
	v_cvt_pk_bf16_f32 v190, v94, v95
	v_cvt_pk_bf16_f32 v191, v96, v97
	global_store_dwordx2 v188, v[190:191], s[36:37]
	s_add_u32 s36, s36, 0x2000
	s_addc_u32 s37, s37, 0
	v_fmamk_f32 v164, v164, 0x3a800000, v202
	v_cmp_gt_f32_e32 vcc, s74, v164
	v_mul_f32_e32 v190, 0x4b800000, v164
	s_nop 0
	v_cndmask_b32_e32 v164, v164, v190, vcc
	v_rsq_f32_e32 v164, v164
	s_nop 0
	v_mul_f32_e32 v190, 0x45800000, v164
	v_cndmask_b32_e32 v164, v164, v190, vcc
	v_mul_f32_e32 v34, v34, v164
	v_mul_f32_e32 v35, v35, v164
	v_mul_f32_e32 v36, v36, v164
	v_mul_f32_e32 v37, v37, v164
	v_fma_f32 v34, v180, v34, v184
	v_fma_f32 v35, v181, v35, v185
	v_fma_f32 v36, v182, v36, v186
	v_fma_f32 v37, v183, v37, v187
	v_cvt_pk_bf16_f32 v190, v34, v35
	v_cvt_pk_bf16_f32 v191, v36, v37
	global_store_dwordx2 v188, v[190:191], s[36:37]
	s_add_u32 s36, s36, 0x2000
	s_addc_u32 s37, s37, 0
	v_fmamk_f32 v165, v165, 0x3a800000, v202
	v_cmp_gt_f32_e32 vcc, s74, v165
	v_mul_f32_e32 v190, 0x4b800000, v165
	s_nop 0
	v_cndmask_b32_e32 v165, v165, v190, vcc
	v_rsq_f32_e32 v165, v165
	s_nop 0
	v_mul_f32_e32 v190, 0x45800000, v165
	v_cndmask_b32_e32 v165, v165, v190, vcc
	v_mul_f32_e32 v38, v38, v165
	v_mul_f32_e32 v39, v39, v165
	v_mul_f32_e32 v40, v40, v165
	v_mul_f32_e32 v41, v41, v165
	v_fma_f32 v38, v180, v38, v184
	v_fma_f32 v39, v181, v39, v185
	v_fma_f32 v40, v182, v40, v186
	v_fma_f32 v41, v183, v41, v187
	v_cvt_pk_bf16_f32 v190, v38, v39
	v_cvt_pk_bf16_f32 v191, v40, v41
	global_store_dwordx2 v188, v[190:191], s[36:37]
	s_add_u32 s36, s36, 0x2000
	s_addc_u32 s37, s37, 0
	v_fmamk_f32 v166, v166, 0x3a800000, v202
	v_cmp_gt_f32_e32 vcc, s74, v166
	v_mul_f32_e32 v190, 0x4b800000, v166
	s_nop 0
	v_cndmask_b32_e32 v166, v166, v190, vcc
	v_rsq_f32_e32 v166, v166
	s_nop 0
	v_mul_f32_e32 v190, 0x45800000, v166
	v_cndmask_b32_e32 v166, v166, v190, vcc
	v_mul_f32_e32 v42, v42, v166
	v_mul_f32_e32 v43, v43, v166
	v_mul_f32_e32 v44, v44, v166
	v_mul_f32_e32 v45, v45, v166
	v_fma_f32 v42, v180, v42, v184
	v_fma_f32 v43, v181, v43, v185
	v_fma_f32 v44, v182, v44, v186
	v_fma_f32 v45, v183, v45, v187
	v_cvt_pk_bf16_f32 v190, v42, v43
	v_cvt_pk_bf16_f32 v191, v44, v45
	global_store_dwordx2 v188, v[190:191], s[36:37]
	s_add_u32 s36, s36, 0x2000
	s_addc_u32 s37, s37, 0
	v_fmamk_f32 v167, v167, 0x3a800000, v202
	v_cmp_gt_f32_e32 vcc, s74, v167
	v_mul_f32_e32 v190, 0x4b800000, v167
	s_nop 0
	v_cndmask_b32_e32 v167, v167, v190, vcc
	v_rsq_f32_e32 v167, v167
	s_nop 0
	v_mul_f32_e32 v190, 0x45800000, v167
	v_cndmask_b32_e32 v167, v167, v190, vcc
	v_mul_f32_e32 v46, v46, v167
	v_mul_f32_e32 v47, v47, v167
	v_mul_f32_e32 v48, v48, v167
	v_mul_f32_e32 v49, v49, v167
	v_fma_f32 v46, v180, v46, v184
	v_fma_f32 v47, v181, v47, v185
	v_fma_f32 v48, v182, v48, v186
	v_fma_f32 v49, v183, v49, v187
	v_cvt_pk_bf16_f32 v190, v46, v47
	v_cvt_pk_bf16_f32 v191, v48, v49
	global_store_dwordx2 v188, v[190:191], s[36:37]
	s_add_u32 s36, s36, 0x2000
	s_addc_u32 s37, s37, 0
	v_fmamk_f32 v168, v168, 0x3a800000, v202
	v_cmp_gt_f32_e32 vcc, s74, v168
	v_mul_f32_e32 v190, 0x4b800000, v168
	s_nop 0
	v_cndmask_b32_e32 v168, v168, v190, vcc
	v_rsq_f32_e32 v168, v168
	s_nop 0
	v_mul_f32_e32 v190, 0x45800000, v168
	v_cndmask_b32_e32 v168, v168, v190, vcc
	v_mul_f32_e32 v50, v50, v168
	v_mul_f32_e32 v51, v51, v168
	v_mul_f32_e32 v52, v52, v168
	v_mul_f32_e32 v53, v53, v168
	v_fma_f32 v50, v180, v50, v184
	v_fma_f32 v51, v181, v51, v185
	v_fma_f32 v52, v182, v52, v186
	v_fma_f32 v53, v183, v53, v187
	v_cvt_pk_bf16_f32 v190, v50, v51
	v_cvt_pk_bf16_f32 v191, v52, v53
	global_store_dwordx2 v188, v[190:191], s[36:37]
	s_add_u32 s36, s36, 0x2000
	s_addc_u32 s37, s37, 0
	v_fmamk_f32 v169, v169, 0x3a800000, v202
	v_cmp_gt_f32_e32 vcc, s74, v169
	v_mul_f32_e32 v190, 0x4b800000, v169
	s_nop 0
	v_cndmask_b32_e32 v169, v169, v190, vcc
	v_rsq_f32_e32 v169, v169
	s_nop 0
	v_mul_f32_e32 v190, 0x45800000, v169
	v_cndmask_b32_e32 v169, v169, v190, vcc
	v_mul_f32_e32 v54, v54, v169
	v_mul_f32_e32 v55, v55, v169
	v_mul_f32_e32 v56, v56, v169
	v_mul_f32_e32 v57, v57, v169
	v_fma_f32 v54, v180, v54, v184
	v_fma_f32 v55, v181, v55, v185
	v_fma_f32 v56, v182, v56, v186
	v_fma_f32 v57, v183, v57, v187
	v_cvt_pk_bf16_f32 v190, v54, v55
	v_cvt_pk_bf16_f32 v191, v56, v57
	global_store_dwordx2 v188, v[190:191], s[36:37]
	s_add_u32 s36, s36, 0x2000
	s_addc_u32 s37, s37, 0
	v_fmamk_f32 v170, v170, 0x3a800000, v202
	v_cmp_gt_f32_e32 vcc, s74, v170
	v_mul_f32_e32 v190, 0x4b800000, v170
	s_nop 0
	v_cndmask_b32_e32 v170, v170, v190, vcc
	v_rsq_f32_e32 v170, v170
	s_nop 0
	v_mul_f32_e32 v190, 0x45800000, v170
	v_cndmask_b32_e32 v170, v170, v190, vcc
	v_mul_f32_e32 v58, v58, v170
	v_mul_f32_e32 v59, v59, v170
	v_mul_f32_e32 v60, v60, v170
	v_mul_f32_e32 v61, v61, v170
	v_fma_f32 v58, v180, v58, v184
	v_fma_f32 v59, v181, v59, v185
	v_fma_f32 v60, v182, v60, v186
	v_fma_f32 v61, v183, v61, v187
	v_cvt_pk_bf16_f32 v190, v58, v59
	v_cvt_pk_bf16_f32 v191, v60, v61
	global_store_dwordx2 v188, v[190:191], s[36:37]
	s_add_u32 s36, s36, 0x2000
	s_addc_u32 s37, s37, 0
	v_fmamk_f32 v171, v171, 0x3a800000, v202
	v_cmp_gt_f32_e32 vcc, s74, v171
	v_mul_f32_e32 v190, 0x4b800000, v171
	s_nop 0
	v_cndmask_b32_e32 v171, v171, v190, vcc
	v_rsq_f32_e32 v171, v171
	s_nop 0
	v_mul_f32_e32 v190, 0x45800000, v171
	v_cndmask_b32_e32 v171, v171, v190, vcc
	v_mul_f32_e32 v62, v62, v171
	v_mul_f32_e32 v63, v63, v171
	v_mul_f32_e32 v64, v64, v171
	v_mul_f32_e32 v65, v65, v171
	v_fma_f32 v62, v180, v62, v184
	v_fma_f32 v63, v181, v63, v185
	v_fma_f32 v64, v182, v64, v186
	v_fma_f32 v65, v183, v65, v187
	v_cvt_pk_bf16_f32 v190, v62, v63
	v_cvt_pk_bf16_f32 v191, v64, v65
	global_store_dwordx2 v188, v[190:191], s[36:37]
	s_add_u32 s36, s36, 0x2000
	s_addc_u32 s37, s37, 0
	v_fmamk_f32 v172, v172, 0x3a800000, v202
	v_cmp_gt_f32_e32 vcc, s74, v172
	v_mul_f32_e32 v190, 0x4b800000, v172
	s_nop 0
	v_cndmask_b32_e32 v172, v172, v190, vcc
	v_rsq_f32_e32 v172, v172
	s_nop 0
	v_mul_f32_e32 v190, 0x45800000, v172
	v_cndmask_b32_e32 v172, v172, v190, vcc
	v_mul_f32_e32 v132, v132, v172
	v_mul_f32_e32 v133, v133, v172
	v_mul_f32_e32 v134, v134, v172
	v_mul_f32_e32 v135, v135, v172
	v_fma_f32 v132, v180, v132, v184
	v_fma_f32 v133, v181, v133, v185
	v_fma_f32 v134, v182, v134, v186
	v_fma_f32 v135, v183, v135, v187
	v_cvt_pk_bf16_f32 v190, v132, v133
	v_cvt_pk_bf16_f32 v191, v134, v135
	global_store_dwordx2 v188, v[190:191], s[36:37]
	s_add_u32 s36, s36, 0x2000
	s_addc_u32 s37, s37, 0
	v_fmamk_f32 v173, v173, 0x3a800000, v202
	v_cmp_gt_f32_e32 vcc, s74, v173
	v_mul_f32_e32 v190, 0x4b800000, v173
	s_nop 0
	v_cndmask_b32_e32 v173, v173, v190, vcc
	v_rsq_f32_e32 v173, v173
	s_nop 0
	v_mul_f32_e32 v190, 0x45800000, v173
	v_cndmask_b32_e32 v173, v173, v190, vcc
	v_mul_f32_e32 v136, v136, v173
	v_mul_f32_e32 v137, v137, v173
	v_mul_f32_e32 v138, v138, v173
	v_mul_f32_e32 v139, v139, v173
	v_fma_f32 v136, v180, v136, v184
	v_fma_f32 v137, v181, v137, v185
	v_fma_f32 v138, v182, v138, v186
	v_fma_f32 v139, v183, v139, v187
	v_cvt_pk_bf16_f32 v190, v136, v137
	v_cvt_pk_bf16_f32 v191, v138, v139
	global_store_dwordx2 v188, v[190:191], s[36:37]
	s_add_u32 s36, s36, 0x2000
	s_addc_u32 s37, s37, 0
	v_fmamk_f32 v174, v174, 0x3a800000, v202
	v_cmp_gt_f32_e32 vcc, s74, v174
	v_mul_f32_e32 v190, 0x4b800000, v174
	s_nop 0
	v_cndmask_b32_e32 v174, v174, v190, vcc
	v_rsq_f32_e32 v174, v174
	s_nop 0
	v_mul_f32_e32 v190, 0x45800000, v174
	v_cndmask_b32_e32 v174, v174, v190, vcc
	v_mul_f32_e32 v140, v140, v174
	v_mul_f32_e32 v141, v141, v174
	v_mul_f32_e32 v142, v142, v174
	v_mul_f32_e32 v143, v143, v174
	v_fma_f32 v140, v180, v140, v184
	v_fma_f32 v141, v181, v141, v185
	v_fma_f32 v142, v182, v142, v186
	v_fma_f32 v143, v183, v143, v187
	v_cvt_pk_bf16_f32 v190, v140, v141
	v_cvt_pk_bf16_f32 v191, v142, v143
	global_store_dwordx2 v188, v[190:191], s[36:37]
	s_add_u32 s36, s36, 0x2000
	s_addc_u32 s37, s37, 0
	v_fmamk_f32 v175, v175, 0x3a800000, v202
	v_cmp_gt_f32_e32 vcc, s74, v175
	v_mul_f32_e32 v190, 0x4b800000, v175
	s_nop 0
	v_cndmask_b32_e32 v175, v175, v190, vcc
	v_rsq_f32_e32 v175, v175
	s_nop 0
	v_mul_f32_e32 v190, 0x45800000, v175
	v_cndmask_b32_e32 v175, v175, v190, vcc
	v_mul_f32_e32 v144, v144, v175
	v_mul_f32_e32 v145, v145, v175
	v_mul_f32_e32 v146, v146, v175
	v_mul_f32_e32 v147, v147, v175
	v_fma_f32 v144, v180, v144, v184
	v_fma_f32 v145, v181, v145, v185
	v_fma_f32 v146, v182, v146, v186
	v_fma_f32 v147, v183, v147, v187
	v_cvt_pk_bf16_f32 v190, v144, v145
	v_cvt_pk_bf16_f32 v191, v146, v147
	global_store_dwordx2 v188, v[190:191], s[36:37]
	s_add_u32 s36, s36, 0x2000
	s_addc_u32 s37, s37, 0
	v_fmamk_f32 v176, v176, 0x3a800000, v202
	v_cmp_gt_f32_e32 vcc, s74, v176
	v_mul_f32_e32 v190, 0x4b800000, v176
	s_nop 0
	v_cndmask_b32_e32 v176, v176, v190, vcc
	v_rsq_f32_e32 v176, v176
	s_nop 0
	v_mul_f32_e32 v190, 0x45800000, v176
	v_cndmask_b32_e32 v176, v176, v190, vcc
	v_mul_f32_e32 v18, v18, v176
	v_mul_f32_e32 v19, v19, v176
	v_mul_f32_e32 v20, v20, v176
	v_mul_f32_e32 v21, v21, v176
	v_fma_f32 v18, v180, v18, v184
	v_fma_f32 v19, v181, v19, v185
	v_fma_f32 v20, v182, v20, v186
	v_fma_f32 v21, v183, v21, v187
	v_cvt_pk_bf16_f32 v190, v18, v19
	v_cvt_pk_bf16_f32 v191, v20, v21
	global_store_dwordx2 v188, v[190:191], s[36:37]
	s_add_u32 s36, s36, 0x2000
	s_addc_u32 s37, s37, 0
	v_fmamk_f32 v177, v177, 0x3a800000, v202
	v_cmp_gt_f32_e32 vcc, s74, v177
	v_mul_f32_e32 v190, 0x4b800000, v177
	s_nop 0
	v_cndmask_b32_e32 v177, v177, v190, vcc
	v_rsq_f32_e32 v177, v177
	s_nop 0
	v_mul_f32_e32 v190, 0x45800000, v177
	v_cndmask_b32_e32 v177, v177, v190, vcc
	v_mul_f32_e32 v22, v22, v177
	v_mul_f32_e32 v23, v23, v177
	v_mul_f32_e32 v24, v24, v177
	v_mul_f32_e32 v25, v25, v177
	v_fma_f32 v22, v180, v22, v184
	v_fma_f32 v23, v181, v23, v185
	v_fma_f32 v24, v182, v24, v186
	v_fma_f32 v25, v183, v25, v187
	v_cvt_pk_bf16_f32 v190, v22, v23
	v_cvt_pk_bf16_f32 v191, v24, v25
	global_store_dwordx2 v188, v[190:191], s[36:37]
	s_add_u32 s36, s36, 0x2000
	s_addc_u32 s37, s37, 0
	v_fmamk_f32 v178, v178, 0x3a800000, v202
	v_cmp_gt_f32_e32 vcc, s74, v178
	v_mul_f32_e32 v190, 0x4b800000, v178
	s_nop 0
	v_cndmask_b32_e32 v178, v178, v190, vcc
	v_rsq_f32_e32 v178, v178
	s_nop 0
	v_mul_f32_e32 v190, 0x45800000, v178
	v_cndmask_b32_e32 v178, v178, v190, vcc
	v_mul_f32_e32 v26, v26, v178
	v_mul_f32_e32 v27, v27, v178
	v_mul_f32_e32 v28, v28, v178
	v_mul_f32_e32 v29, v29, v178
	v_fma_f32 v26, v180, v26, v184
	v_fma_f32 v27, v181, v27, v185
	v_fma_f32 v28, v182, v28, v186
	v_fma_f32 v29, v183, v29, v187
	v_cvt_pk_bf16_f32 v190, v26, v27
	v_cvt_pk_bf16_f32 v191, v28, v29
	global_store_dwordx2 v188, v[190:191], s[36:37]
	s_add_u32 s36, s36, 0x2000
	s_addc_u32 s37, s37, 0
	v_fmamk_f32 v179, v179, 0x3a800000, v202
	v_cmp_gt_f32_e32 vcc, s74, v179
	v_mul_f32_e32 v190, 0x4b800000, v179
	s_nop 0
	v_cndmask_b32_e32 v179, v179, v190, vcc
	v_rsq_f32_e32 v179, v179
	s_nop 0
	v_mul_f32_e32 v190, 0x45800000, v179
	v_cndmask_b32_e32 v179, v179, v190, vcc
	v_mul_f32_e32 v30, v30, v179
	v_mul_f32_e32 v31, v31, v179
	v_mul_f32_e32 v32, v32, v179
	v_mul_f32_e32 v33, v33, v179
	v_fma_f32 v30, v180, v30, v184
	v_fma_f32 v31, v181, v31, v185
	v_fma_f32 v32, v182, v32, v186
	v_fma_f32 v33, v183, v33, v187
	v_cvt_pk_bf16_f32 v190, v30, v31
	v_cvt_pk_bf16_f32 v191, v32, v33
	global_store_dwordx2 v188, v[190:191], s[36:37]
	s_add_u32 s36, s36, 0x2000
	s_addc_u32 s37, s37, 0
	s_movk_i32 s38, 0x1e00
	s_branch .LBB0_206
